# v39 plus: in the GEMM K-loops the m0 write is moved in front of the address add of each LDS-DMA so the s_nop pad behind it can go (40 sites)
# speedup vs baseline: 1.0048x; 1.0024x over previous
; #define PG8_STAGE(bufoff, gbase, voff) do { _Pragma("unroll") for (int _i = 0; _i < 2; ++_i) \
;         __builtin_amdgcn_global_load_lds((const unsigned*)((const char*)(gbase) + (voff)[_i]), (PG8_LAS unsigned*)(lds + (bufoff) + ldsw + _i * 8192), 16, 0, 0); } while (0)
; #define PG8_LDA(dst, b, h) do { _Pragma("unroll") for (int m = 0; m < 4; ++m) _Pragma("unroll") for (int k = 0; k < 2; ++k) dst[m][k] = *(const PG8_LAS bf16x8*)(lds + PG8_SA(b, h) + aoff + m * 2048 + k * 1024); } while (0)
; #define PG8_LDB(dst, b, h) do { _Pragma("unroll") for (int n = 0; n < 2; ++n) _Pragma("unroll") for (int k = 0; k < 2; ++k) dst[n][k] = *(const PG8_LAS bf16x8*)(lds + PG8_SB(b, h) + boff + n * 2048 + k * 1024); } while (0)
; #define PG8_MMA(ai, bj, At, Bt) do { __builtin_amdgcn_s_setprio(1); _Pragma("unroll") for (int m = 0; m < 4; ++m) _Pragma("unroll") for (int n = 0; n < 2; ++n) _Pragma("unroll") for (int k = 0; k < 2; ++k) \
;         acc[ai][bj][m][n] = __builtin_amdgcn_mfma_f32_16x16x32_bf16(Bt[n][k], At[m][k], acc[ai][bj][m][n], 0, 0, 0); __builtin_amdgcn_s_setprio(0); } while (0)
; #define PG8_WAIT_V(n) asm volatile("s_waitcnt vmcnt(" #n ")" ::: "memory")
; #define PG8_WAIT_L(n) asm volatile("s_waitcnt lgkmcnt(" #n ")" ::: "memory")
; #define PG8_BAR __builtin_amdgcn_s_barrier()
; template <class Epi, class Sched, bool ALIGN_EPI = false, bool SP2 = false>
; __device__ __forceinline__ void gemm_phase(PG8_LAS unsigned char* lds, const Gemm g, const Sched& S, const Epi& E) {
;     ...
;             const char* a1 = cA + (size_t)(t + 1) * kstep;
;             const char* a2 = last ? nA : cA + (size_t)(t + 2) * kstep; const char* b2 = last ? nB : cB + (size_t)(t + 2) * kstep;
;             const char* a3 = a2 + kstep; const char* b3 = b2 + kstep;
;             if (last && has_next) S.a_ready(nxt);
;             if constexpr (SP2) {
;             PG8_LDB(B0, 0, 0); PG8_LDB(B1, 0, 1); PG8_SCHED; PG8_LDA(At, 0, 0); PG8_STAGE(PG8_SA(1, 1), a1 + hstep, voffA);
;             PG8_WAIT_V(8); PG8_WAIT_L(0); PG8_BAR; PG8_MMA(0, 0, At, B0); PG8_MMA(0, 1, At, B1); PG8_BAR; PG8_SCHED;
;             PG8_LDA(At, 0, 1); PG8_STAGE(PG8_SB(0, 0), b2, voffB); PG8_STAGE(PG8_SB(0, 1), b2 + hstepB, voffB); PG8_STAGE(PG8_SA(0, 0), a2, voffA);
;             PG8_WAIT_V(8); PG8_WAIT_L(0); PG8_BAR; PG8_MMA(1, 0, At, B0); PG8_MMA(1, 1, At, B1); PG8_BAR; PG8_SCHED;
.LBB0_170:
	s_add_u32 s9, s70, s46
	s_addc_u32 s10, s71, s47
	s_add_u32 s9, s9, 0x100
	s_addc_u32 s10, s10, 0
	s_add_u32 s11, s93, s46
	s_addc_u32 s12, s94, s47
	s_add_i32 s13, 0, 0x10000
	s_cmpk_eq_i32 s46, 0xf00
	s_cselect_b32 s85, s4, s10
	s_cselect_b32 s84, s5, s9
	s_cselect_b32 s81, s6, s12
	s_cselect_b32 s80, s7, s11
	s_add_i32 s9, 0, 0x14000
	v_add_u32_e32 v160, s13, v139
	v_add_u32_e32 v178, s9, v139
	ds_read_b128 v[148:151], v160
	ds_read_b128 v[152:155], v160 offset:1024
	ds_read_b128 v[156:159], v160 offset:2048
	ds_read_b128 v[160:163], v160 offset:3072
	ds_read_b128 v[166:169], v178
	ds_read_b128 v[170:173], v178 offset:1024
	ds_read_b128 v[174:177], v178 offset:2048
	ds_read_b128 v[178:181], v178 offset:3072
	v_lshl_add_u64 v[194:195], v[144:145], 0, s[46:47]
	s_add_i32 m0, s1, 0xc000
	ds_read_b128 v[182:185], v165
	ds_read_b128 v[206:209], v165 offset:1024
	ds_read_b128 v[210:213], v165 offset:2048
	ds_read_b128 v[214:217], v165 offset:3072
	ds_read_b128 v[218:221], v165 offset:4096
	ds_read_b128 v[236:239], v165 offset:5120
	ds_read_b128 v[240:243], v165 offset:6144
	ds_read_b128 v[244:247], v165 offset:7168
	global_load_lds_dwordx4 v[194:195], off
	s_add_i32 m0, s1, 0xe000
	v_lshl_add_u64 v[194:195], v[146:147], 0, s[46:47]
	global_load_lds_dwordx4 v[194:195], off
	s_waitcnt vmcnt(8)
	s_waitcnt lgkmcnt(0)
	s_barrier
	v_mfma_f32_16x16x32_bf16 v[126:129], v[148:151], v[182:185], v[126:129]
	v_mfma_f32_16x16x32_bf16 v[122:125], v[156:159], v[182:185], v[122:125]
	v_mfma_f32_16x16x32_bf16 v[118:121], v[148:151], v[210:213], v[118:121]
	v_mfma_f32_16x16x32_bf16 v[114:117], v[156:159], v[210:213], v[114:117]
	v_mfma_f32_16x16x32_bf16 v[110:113], v[148:151], v[218:221], v[110:113]
	v_mfma_f32_16x16x32_bf16 v[106:109], v[156:159], v[218:221], v[106:109]
	v_mfma_f32_16x16x32_bf16 v[102:105], v[148:151], v[240:243], v[102:105]
	v_mfma_f32_16x16x32_bf16 v[98:101], v[156:159], v[240:243], v[98:101]
	v_mfma_f32_16x16x32_bf16 v[126:129], v[152:155], v[206:209], v[126:129]
	v_mfma_f32_16x16x32_bf16 v[122:125], v[160:163], v[206:209], v[122:125]
	v_mfma_f32_16x16x32_bf16 v[118:121], v[152:155], v[214:217], v[118:121]
	v_mfma_f32_16x16x32_bf16 v[114:117], v[160:163], v[214:217], v[114:117]
	v_mfma_f32_16x16x32_bf16 v[110:113], v[152:155], v[236:239], v[110:113]
	v_mfma_f32_16x16x32_bf16 v[106:109], v[160:163], v[236:239], v[106:109]
	v_mfma_f32_16x16x32_bf16 v[102:105], v[152:155], v[244:247], v[102:105]
	v_mfma_f32_16x16x32_bf16 v[98:101], v[160:163], v[244:247], v[98:101]
	v_mfma_f32_16x16x32_bf16 v[94:97], v[166:169], v[182:185], v[94:97]
	v_mfma_f32_16x16x32_bf16 v[90:93], v[174:177], v[182:185], v[90:93]
	v_mfma_f32_16x16x32_bf16 v[86:89], v[166:169], v[210:213], v[86:89]
	v_mfma_f32_16x16x32_bf16 v[82:85], v[174:177], v[210:213], v[82:85]
	v_mfma_f32_16x16x32_bf16 v[78:81], v[166:169], v[218:221], v[78:81]
	v_mfma_f32_16x16x32_bf16 v[74:77], v[174:177], v[218:221], v[74:77]
	v_mfma_f32_16x16x32_bf16 v[70:73], v[166:169], v[240:243], v[70:73]
	v_mfma_f32_16x16x32_bf16 v[66:69], v[174:177], v[240:243], v[66:69]
	v_mfma_f32_16x16x32_bf16 v[94:97], v[170:173], v[206:209], v[94:97]
	v_mfma_f32_16x16x32_bf16 v[90:93], v[178:181], v[206:209], v[90:93]
	v_mfma_f32_16x16x32_bf16 v[86:89], v[170:173], v[214:217], v[86:89]
	v_mfma_f32_16x16x32_bf16 v[82:85], v[178:181], v[214:217], v[82:85]
	v_mfma_f32_16x16x32_bf16 v[78:81], v[170:173], v[236:239], v[78:81]
	v_mfma_f32_16x16x32_bf16 v[74:77], v[178:181], v[236:239], v[74:77]
	v_mfma_f32_16x16x32_bf16 v[70:73], v[170:173], v[244:247], v[70:73]
	v_mfma_f32_16x16x32_bf16 v[66:69], v[178:181], v[244:247], v[66:69]
	s_barrier
	s_add_i32 s10, s13, s0
	v_lshl_add_u64 v[194:195], s[80:81], 0, v[132:133]
	s_mov_b32 m0, s10
	ds_read_b128 v[182:185], v165 offset:16384
	ds_read_b128 v[206:209], v165 offset:17408
	ds_read_b128 v[210:213], v165 offset:18432
	ds_read_b128 v[214:217], v165 offset:19456
	ds_read_b128 v[218:221], v165 offset:20480
	ds_read_b128 v[236:239], v165 offset:21504
	ds_read_b128 v[240:243], v165 offset:22528
	ds_read_b128 v[244:247], v165 offset:23552
	global_load_lds_dwordx4 v[194:195], off
	s_add_i32 m0, s10, 0x2000
	s_add_u32 s10, s80, 0x20000
	v_lshl_add_u64 v[196:197], s[80:81], 0, v[136:137]
	s_addc_u32 s11, s81, 0
	s_add_i32 s9, s9, s0
	global_load_lds_dwordx4 v[196:197], off
	v_lshl_add_u64 v[222:223], s[10:11], 0, v[132:133]
	s_mov_b32 m0, s9
	v_lshl_add_u64 v[234:235], s[84:85], 0, v[134:135]
	global_load_lds_dwordx4 v[222:223], off
	s_add_i32 m0, s9, 0x2000
	v_lshl_add_u64 v[222:223], s[10:11], 0, v[136:137]
	global_load_lds_dwordx4 v[222:223], off
	s_mov_b32 m0, s1
	v_lshl_add_u64 v[222:223], s[84:85], 0, v[130:131]
	global_load_lds_dwordx4 v[222:223], off
	s_mov_b32 m0, s25
	s_nop 0
	global_load_lds_dwordx4 v[234:235], off
	s_waitcnt vmcnt(8)
	s_waitcnt lgkmcnt(0)
	s_barrier
; #define PG8_STAGE(bufoff, gbase, voff) do { _Pragma("unroll") for (int _i = 0; _i < 2; ++_i) \
;         __builtin_amdgcn_global_load_lds((const unsigned*)((const char*)(gbase) + (voff)[_i]), (PG8_LAS unsigned*)(lds + (bufoff) + ldsw + _i * 8192), 16, 0, 0); } while (0)
; #define PG8_LDA(dst, b, h) do { _Pragma("unroll") for (int m = 0; m < 4; ++m) _Pragma("unroll") for (int k = 0; k < 2; ++k) dst[m][k] = *(const PG8_LAS bf16x8*)(lds + PG8_SA(b, h) + aoff + m * 2048 + k * 1024); } while (0)
; #define PG8_LDB(dst, b, h) do { _Pragma("unroll") for (int n = 0; n < 2; ++n) _Pragma("unroll") for (int k = 0; k < 2; ++k) dst[n][k] = *(const PG8_LAS bf16x8*)(lds + PG8_SB(b, h) + boff + n * 2048 + k * 1024); } while (0)
; #define PG8_MMA(ai, bj, At, Bt) do { __builtin_amdgcn_s_setprio(1); _Pragma("unroll") for (int m = 0; m < 4; ++m) _Pragma("unroll") for (int n = 0; n < 2; ++n) _Pragma("unroll") for (int k = 0; k < 2; ++k) \
;         acc[ai][bj][m][n] = __builtin_amdgcn_mfma_f32_16x16x32_bf16(Bt[n][k], At[m][k], acc[ai][bj][m][n], 0, 0, 0); __builtin_amdgcn_s_setprio(0); } while (0)
; #define PG8_WAIT_V(n) asm volatile("s_waitcnt vmcnt(" #n ")" ::: "memory")
; #define PG8_WAIT_L(n) asm volatile("s_waitcnt lgkmcnt(" #n ")" ::: "memory")
; #define PG8_BAR __builtin_amdgcn_s_barrier()
; #define PG8_SCHED __builtin_amdgcn_sched_barrier(0)
; template <class Epi, class Sched, bool ALIGN_EPI = false, bool SP2 = false>
; __device__ __forceinline__ void gemm_phase(PG8_LAS unsigned char* lds, const Gemm g, const Sched& S, const Epi& E) {
;     ...
;             PG8_WAIT_V(8); PG8_WAIT_L(0); PG8_BAR; PG8_MMA(1, 0, At, B0); PG8_MMA(1, 1, At, B1); PG8_BAR; PG8_SCHED;
;             PG8_LDB(B0, 1, 0); PG8_LDB(B1, 1, 1); PG8_SCHED; PG8_LDA(At, 1, 0); PG8_STAGE(PG8_SA(0, 1), a2 + hstep, voffA);
;             PG8_WAIT_V(8); PG8_WAIT_L(0); PG8_BAR; PG8_MMA(0, 0, At, B0); PG8_MMA(0, 1, At, B1); PG8_BAR; PG8_SCHED;
	v_mfma_f32_16x16x32_bf16 v[62:65], v[148:151], v[182:185], v[62:65]
	v_mfma_f32_16x16x32_bf16 v[58:61], v[156:159], v[182:185], v[58:61]
	v_mfma_f32_16x16x32_bf16 v[54:57], v[148:151], v[210:213], v[54:57]
	v_mfma_f32_16x16x32_bf16 v[50:53], v[156:159], v[210:213], v[50:53]
	v_mfma_f32_16x16x32_bf16 v[46:49], v[148:151], v[218:221], v[46:49]
	v_mfma_f32_16x16x32_bf16 v[42:45], v[156:159], v[218:221], v[42:45]
	v_mfma_f32_16x16x32_bf16 v[38:41], v[148:151], v[240:243], v[38:41]
	v_mfma_f32_16x16x32_bf16 v[34:37], v[156:159], v[240:243], v[34:37]
	v_mfma_f32_16x16x32_bf16 v[62:65], v[152:155], v[206:209], v[62:65]
	v_mfma_f32_16x16x32_bf16 v[58:61], v[160:163], v[206:209], v[58:61]
	v_mfma_f32_16x16x32_bf16 v[54:57], v[152:155], v[214:217], v[54:57]
	v_mfma_f32_16x16x32_bf16 v[50:53], v[160:163], v[214:217], v[50:53]
	v_mfma_f32_16x16x32_bf16 v[46:49], v[152:155], v[236:239], v[46:49]
	v_mfma_f32_16x16x32_bf16 v[42:45], v[160:163], v[236:239], v[42:45]
	v_mfma_f32_16x16x32_bf16 v[38:41], v[152:155], v[244:247], v[38:41]
	v_mfma_f32_16x16x32_bf16 v[34:37], v[160:163], v[244:247], v[34:37]
	v_mfma_f32_16x16x32_bf16 v[30:33], v[166:169], v[182:185], v[30:33]
	v_mfma_f32_16x16x32_bf16 v[26:29], v[174:177], v[182:185], v[26:29]
	v_mfma_f32_16x16x32_bf16 v[22:25], v[166:169], v[210:213], v[22:25]
	v_mfma_f32_16x16x32_bf16 v[18:21], v[174:177], v[210:213], v[18:21]
	v_mfma_f32_16x16x32_bf16 v[14:17], v[166:169], v[218:221], v[14:17]
	v_mfma_f32_16x16x32_bf16 v[10:13], v[174:177], v[218:221], v[10:13]
	v_mfma_f32_16x16x32_bf16 v[6:9], v[166:169], v[240:243], v[6:9]
	v_mfma_f32_16x16x32_bf16 v[2:5], v[174:177], v[240:243], v[2:5]
	v_mfma_f32_16x16x32_bf16 v[30:33], v[170:173], v[206:209], v[30:33]
	v_mfma_f32_16x16x32_bf16 v[26:29], v[178:181], v[206:209], v[26:29]
	v_mfma_f32_16x16x32_bf16 v[22:25], v[170:173], v[214:217], v[22:25]
	v_mfma_f32_16x16x32_bf16 v[18:21], v[178:181], v[214:217], v[18:21]
	v_mfma_f32_16x16x32_bf16 v[14:17], v[170:173], v[236:239], v[14:17]
	v_mfma_f32_16x16x32_bf16 v[10:13], v[178:181], v[236:239], v[10:13]
	v_mfma_f32_16x16x32_bf16 v[6:9], v[170:173], v[244:247], v[6:9]
	v_mfma_f32_16x16x32_bf16 v[2:5], v[178:181], v[244:247], v[2:5]
	s_barrier
	s_add_i32 s9, 0, 0x18000
	s_add_i32 s12, 0, 0x1c000
	v_add_u32_e32 v160, s9, v139
	v_add_u32_e32 v178, s12, v139
	ds_read_b128 v[148:151], v160
	ds_read_b128 v[152:155], v160 offset:1024
	ds_read_b128 v[156:159], v160 offset:2048
	ds_read_b128 v[160:163], v160 offset:3072
	ds_read_b128 v[166:169], v178
	ds_read_b128 v[170:173], v178 offset:1024
	ds_read_b128 v[174:177], v178 offset:2048
	ds_read_b128 v[178:181], v178 offset:3072
	s_add_u32 s10, s84, 0x80000
	s_addc_u32 s11, s85, 0
	s_mov_b32 m0, s42
	v_lshl_add_u64 v[198:199], s[10:11], 0, v[130:131]
	ds_read_b128 v[182:185], v165 offset:32768
	ds_read_b128 v[206:209], v165 offset:33792
	ds_read_b128 v[210:213], v165 offset:34816
	ds_read_b128 v[214:217], v165 offset:35840
	ds_read_b128 v[218:221], v165 offset:36864
	ds_read_b128 v[236:239], v165 offset:37888
	ds_read_b128 v[240:243], v165 offset:38912
	ds_read_b128 v[244:247], v165 offset:39936
	global_load_lds_dwordx4 v[198:199], off
	s_mov_b32 m0, s51
	v_lshl_add_u64 v[198:199], s[10:11], 0, v[134:135]
	global_load_lds_dwordx4 v[198:199], off
	s_waitcnt vmcnt(8)
	s_waitcnt lgkmcnt(0)
	s_barrier
	v_mfma_f32_16x16x32_bf16 v[126:129], v[148:151], v[182:185], v[126:129]
	v_mfma_f32_16x16x32_bf16 v[122:125], v[156:159], v[182:185], v[122:125]
	v_mfma_f32_16x16x32_bf16 v[118:121], v[148:151], v[210:213], v[118:121]
	v_mfma_f32_16x16x32_bf16 v[114:117], v[156:159], v[210:213], v[114:117]
	v_mfma_f32_16x16x32_bf16 v[110:113], v[148:151], v[218:221], v[110:113]
	v_mfma_f32_16x16x32_bf16 v[106:109], v[156:159], v[218:221], v[106:109]
	v_mfma_f32_16x16x32_bf16 v[102:105], v[148:151], v[240:243], v[102:105]
	v_mfma_f32_16x16x32_bf16 v[98:101], v[156:159], v[240:243], v[98:101]
	v_mfma_f32_16x16x32_bf16 v[126:129], v[152:155], v[206:209], v[126:129]
	v_mfma_f32_16x16x32_bf16 v[122:125], v[160:163], v[206:209], v[122:125]
	v_mfma_f32_16x16x32_bf16 v[118:121], v[152:155], v[214:217], v[118:121]
	v_mfma_f32_16x16x32_bf16 v[114:117], v[160:163], v[214:217], v[114:117]
	v_mfma_f32_16x16x32_bf16 v[110:113], v[152:155], v[236:239], v[110:113]
	v_mfma_f32_16x16x32_bf16 v[106:109], v[160:163], v[236:239], v[106:109]
	v_mfma_f32_16x16x32_bf16 v[102:105], v[152:155], v[244:247], v[102:105]
	v_mfma_f32_16x16x32_bf16 v[98:101], v[160:163], v[244:247], v[98:101]
	v_mfma_f32_16x16x32_bf16 v[94:97], v[166:169], v[182:185], v[94:97]
	v_mfma_f32_16x16x32_bf16 v[90:93], v[174:177], v[182:185], v[90:93]
	v_mfma_f32_16x16x32_bf16 v[86:89], v[166:169], v[210:213], v[86:89]
	v_mfma_f32_16x16x32_bf16 v[82:85], v[174:177], v[210:213], v[82:85]
	v_mfma_f32_16x16x32_bf16 v[78:81], v[166:169], v[218:221], v[78:81]
	v_mfma_f32_16x16x32_bf16 v[74:77], v[174:177], v[218:221], v[74:77]
	v_mfma_f32_16x16x32_bf16 v[70:73], v[166:169], v[240:243], v[70:73]
	v_mfma_f32_16x16x32_bf16 v[66:69], v[174:177], v[240:243], v[66:69]
	v_mfma_f32_16x16x32_bf16 v[94:97], v[170:173], v[206:209], v[94:97]
	v_mfma_f32_16x16x32_bf16 v[90:93], v[178:181], v[206:209], v[90:93]
	v_mfma_f32_16x16x32_bf16 v[86:89], v[170:173], v[214:217], v[86:89]
	v_mfma_f32_16x16x32_bf16 v[82:85], v[178:181], v[214:217], v[82:85]
	v_mfma_f32_16x16x32_bf16 v[78:81], v[170:173], v[236:239], v[78:81]
	v_mfma_f32_16x16x32_bf16 v[74:77], v[178:181], v[236:239], v[74:77]
	v_mfma_f32_16x16x32_bf16 v[70:73], v[170:173], v[244:247], v[70:73]
	v_mfma_f32_16x16x32_bf16 v[66:69], v[178:181], v[244:247], v[66:69]
	s_barrier
; #define PG8_STAGE(bufoff, gbase, voff) do { _Pragma("unroll") for (int _i = 0; _i < 2; ++_i) \
;         __builtin_amdgcn_global_load_lds((const unsigned*)((const char*)(gbase) + (voff)[_i]), (PG8_LAS unsigned*)(lds + (bufoff) + ldsw + _i * 8192), 16, 0, 0); } while (0)
; #define PG8_LDA(dst, b, h) do { _Pragma("unroll") for (int m = 0; m < 4; ++m) _Pragma("unroll") for (int k = 0; k < 2; ++k) dst[m][k] = *(const PG8_LAS bf16x8*)(lds + PG8_SA(b, h) + aoff + m * 2048 + k * 1024); } while (0)
; #define PG8_MMA(ai, bj, At, Bt) do { __builtin_amdgcn_s_setprio(1); _Pragma("unroll") for (int m = 0; m < 4; ++m) _Pragma("unroll") for (int n = 0; n < 2; ++n) _Pragma("unroll") for (int k = 0; k < 2; ++k) \
;         acc[ai][bj][m][n] = __builtin_amdgcn_mfma_f32_16x16x32_bf16(Bt[n][k], At[m][k], acc[ai][bj][m][n], 0, 0, 0); __builtin_amdgcn_s_setprio(0); } while (0)
; #define PG8_WAIT_V(n) asm volatile("s_waitcnt vmcnt(" #n ")" ::: "memory")
; #define PG8_WAIT_L(n) asm volatile("s_waitcnt lgkmcnt(" #n ")" ::: "memory")
; #define PG8_BAR __builtin_amdgcn_s_barrier()
; #define PG8_SCHED __builtin_amdgcn_sched_barrier(0)
; template <class Epi, class Sched, bool ALIGN_EPI = false, bool SP2 = false>
; __device__ __forceinline__ void gemm_phase(PG8_LAS unsigned char* lds, const Gemm g, const Sched& S, const Epi& E) {
;     ...
;             PG8_LDA(At, 1, 1); PG8_STAGE(PG8_SB(1, 0), b3, voffB); PG8_STAGE(PG8_SB(1, 1), b3 + hstepB, voffB); PG8_STAGE(PG8_SA(1, 0), a3, voffA);
;             PG8_WAIT_V(8); PG8_WAIT_L(0); PG8_BAR; PG8_MMA(1, 0, At, B0); PG8_MMA(1, 1, At, B1); PG8_BAR; PG8_SCHED;
	s_add_i32 s9, s9, s0
	v_lshl_add_u64 v[194:195], v[194:195], 0, s[60:61]
	s_mov_b32 m0, s9
	ds_read_b128 v[182:185], v165 offset:49152
	ds_read_b128 v[206:209], v165 offset:50176
	ds_read_b128 v[210:213], v165 offset:51200
	ds_read_b128 v[214:217], v165 offset:52224
	ds_read_b128 v[218:221], v165 offset:53248
	ds_read_b128 v[236:239], v165 offset:54272
	ds_read_b128 v[240:243], v165 offset:55296
	ds_read_b128 v[244:247], v165 offset:56320
	global_load_lds_dwordx4 v[194:195], off
	s_add_i32 m0, s9, 0x2000
	s_add_u32 s10, s80, 0x20080
	v_lshl_add_u64 v[194:195], v[196:197], 0, s[60:61]
	s_addc_u32 s11, s81, 0
	s_add_i32 s9, s12, s0
	global_load_lds_dwordx4 v[194:195], off
	s_mov_b32 m0, s9
	v_lshl_add_u64 v[194:195], s[10:11], 0, v[132:133]
	global_load_lds_dwordx4 v[194:195], off
	s_add_i32 m0, s9, 0x2000
	v_lshl_add_u64 v[194:195], s[10:11], 0, v[136:137]
	global_load_lds_dwordx4 v[194:195], off
	s_mov_b32 m0, s66
	v_lshl_add_u64 v[194:195], v[222:223], 0, s[60:61]
	global_load_lds_dwordx4 v[194:195], off
	s_mov_b32 m0, s67
	v_lshl_add_u64 v[194:195], v[234:235], 0, s[60:61]
	global_load_lds_dwordx4 v[194:195], off
	s_waitcnt vmcnt(8)
	s_waitcnt lgkmcnt(0)
	s_barrier
	v_mfma_f32_16x16x32_bf16 v[62:65], v[148:151], v[182:185], v[62:65]
	v_mfma_f32_16x16x32_bf16 v[58:61], v[156:159], v[182:185], v[58:61]
	v_mfma_f32_16x16x32_bf16 v[54:57], v[148:151], v[210:213], v[54:57]
	v_mfma_f32_16x16x32_bf16 v[50:53], v[156:159], v[210:213], v[50:53]
	v_mfma_f32_16x16x32_bf16 v[46:49], v[148:151], v[218:221], v[46:49]
	v_mfma_f32_16x16x32_bf16 v[42:45], v[156:159], v[218:221], v[42:45]
	v_mfma_f32_16x16x32_bf16 v[38:41], v[148:151], v[240:243], v[38:41]
	v_mfma_f32_16x16x32_bf16 v[34:37], v[156:159], v[240:243], v[34:37]
	v_mfma_f32_16x16x32_bf16 v[62:65], v[152:155], v[206:209], v[62:65]
	v_mfma_f32_16x16x32_bf16 v[58:61], v[160:163], v[206:209], v[58:61]
	v_mfma_f32_16x16x32_bf16 v[54:57], v[152:155], v[214:217], v[54:57]
	v_mfma_f32_16x16x32_bf16 v[50:53], v[160:163], v[214:217], v[50:53]
	v_mfma_f32_16x16x32_bf16 v[46:49], v[152:155], v[236:239], v[46:49]
	v_mfma_f32_16x16x32_bf16 v[42:45], v[160:163], v[236:239], v[42:45]
	v_mfma_f32_16x16x32_bf16 v[38:41], v[152:155], v[244:247], v[38:41]
	v_mfma_f32_16x16x32_bf16 v[34:37], v[160:163], v[244:247], v[34:37]
	v_mfma_f32_16x16x32_bf16 v[30:33], v[166:169], v[182:185], v[30:33]
	v_mfma_f32_16x16x32_bf16 v[26:29], v[174:177], v[182:185], v[26:29]
	v_mfma_f32_16x16x32_bf16 v[22:25], v[166:169], v[210:213], v[22:25]
	v_mfma_f32_16x16x32_bf16 v[18:21], v[174:177], v[210:213], v[18:21]
	v_mfma_f32_16x16x32_bf16 v[14:17], v[166:169], v[218:221], v[14:17]
	v_mfma_f32_16x16x32_bf16 v[10:13], v[174:177], v[218:221], v[10:13]
	v_mfma_f32_16x16x32_bf16 v[6:9], v[166:169], v[240:243], v[6:9]
	v_mfma_f32_16x16x32_bf16 v[2:5], v[174:177], v[240:243], v[2:5]
	v_mfma_f32_16x16x32_bf16 v[30:33], v[170:173], v[206:209], v[30:33]
	v_mfma_f32_16x16x32_bf16 v[26:29], v[178:181], v[206:209], v[26:29]
	v_mfma_f32_16x16x32_bf16 v[22:25], v[170:173], v[214:217], v[22:25]
	v_mfma_f32_16x16x32_bf16 v[18:21], v[178:181], v[214:217], v[18:21]
	v_mfma_f32_16x16x32_bf16 v[14:17], v[170:173], v[236:239], v[14:17]
	v_mfma_f32_16x16x32_bf16 v[10:13], v[178:181], v[236:239], v[10:13]
	v_mfma_f32_16x16x32_bf16 v[6:9], v[170:173], v[244:247], v[6:9]
	v_mfma_f32_16x16x32_bf16 v[2:5], v[178:181], v[244:247], v[2:5]
	s_barrier
	s_add_i32 s8, s8, 2
	s_add_u32 s46, s46, 0x100
	s_addc_u32 s47, s47, 0
	s_cmp_gt_u32 s8, 29
	s_cbranch_scc0 .LBB0_170
	s_and_b64 vcc, exec, s[54:55]
	s_cbranch_vccz .LBB0_173
	s_barrier

; #define PG8_STAGE(bufoff, gbase, voff) do { _Pragma("unroll") for (int _i = 0; _i < 2; ++_i) \
;         __builtin_amdgcn_global_load_lds((const unsigned*)((const char*)(gbase) + (voff)[_i]), (PG8_LAS unsigned*)(lds + (bufoff) + ldsw + _i * 8192), 16, 0, 0); } while (0)
; #define PG8_LDA(dst, b, h) do { _Pragma("unroll") for (int m = 0; m < 4; ++m) _Pragma("unroll") for (int k = 0; k < 2; ++k) dst[m][k] = *(const PG8_LAS bf16x8*)(lds + PG8_SA(b, h) + aoff + m * 2048 + k * 1024); } while (0)
; #define PG8_LDB(dst, b, h) do { _Pragma("unroll") for (int n = 0; n < 2; ++n) _Pragma("unroll") for (int k = 0; k < 2; ++k) dst[n][k] = *(const PG8_LAS bf16x8*)(lds + PG8_SB(b, h) + boff + n * 2048 + k * 1024); } while (0)
; #define PG8_MMA(ai, bj, At, Bt) do { __builtin_amdgcn_s_setprio(1); _Pragma("unroll") for (int m = 0; m < 4; ++m) _Pragma("unroll") for (int n = 0; n < 2; ++n) _Pragma("unroll") for (int k = 0; k < 2; ++k) \
;         acc[ai][bj][m][n] = __builtin_amdgcn_mfma_f32_16x16x32_bf16(Bt[n][k], At[m][k], acc[ai][bj][m][n], 0, 0, 0); __builtin_amdgcn_s_setprio(0); } while (0)
; #define PG8_WAIT_V(n) asm volatile("s_waitcnt vmcnt(" #n ")" ::: "memory")
; #define PG8_WAIT_L(n) asm volatile("s_waitcnt lgkmcnt(" #n ")" ::: "memory")
; #define PG8_BAR __builtin_amdgcn_s_barrier()
; template <class Epi, class Sched, bool ALIGN_EPI = false, bool SP2 = false>
; __device__ __forceinline__ void gemm_phase(PG8_LAS unsigned char* lds, const Gemm g, const Sched& S, const Epi& E) {
;     ...
;             const char* a1 = cA + (size_t)(t + 1) * kstep;
;             const char* a2 = last ? nA : cA + (size_t)(t + 2) * kstep; const char* b2 = last ? nB : cB + (size_t)(t + 2) * kstep;
;             const char* a3 = a2 + kstep; const char* b3 = b2 + kstep;
;             if (last && has_next) S.a_ready(nxt);
;             if constexpr (SP2) {
;             PG8_LDB(B0, 0, 0); PG8_LDB(B1, 0, 1); PG8_SCHED; PG8_LDA(At, 0, 0); PG8_STAGE(PG8_SA(1, 1), a1 + hstep, voffA);
;             PG8_WAIT_V(8); PG8_WAIT_L(0); PG8_BAR; PG8_MMA(0, 0, At, B0); PG8_MMA(0, 1, At, B1); PG8_BAR; PG8_SCHED;
;             PG8_LDA(At, 0, 1); PG8_STAGE(PG8_SB(0, 0), b2, voffB); PG8_STAGE(PG8_SB(0, 1), b2 + hstepB, voffB); PG8_STAGE(PG8_SA(0, 0), a2, voffA);
;             PG8_WAIT_V(8); PG8_WAIT_L(0); PG8_BAR; PG8_MMA(1, 0, At, B0); PG8_MMA(1, 1, At, B1); PG8_BAR; PG8_SCHED;
.LBB0_788:
	s_add_u32 s9, s68, 0xfffe0080
	s_addc_u32 s10, s69, -1
	s_add_i32 s11, 0, 0x10000
	s_cmp_eq_u32 s8, 4
	s_cselect_b32 s77, s36, s10
	s_cselect_b32 s76, s37, s9
	s_cselect_b32 s73, s4, s7
	s_cselect_b32 s72, s5, s6
	s_add_i32 s9, 0, 0x14000
	v_add_u32_e32 v54, s11, v193
	v_add_u32_e32 v150, s9, v193
	ds_read_b128 v[34:37], v54
	ds_read_b128 v[38:41], v54 offset:1024
	ds_read_b128 v[50:53], v54 offset:2048
	ds_read_b128 v[54:57], v54 offset:3072
	ds_read_b128 v[114:117], v150
	ds_read_b128 v[126:129], v150 offset:1024
	ds_read_b128 v[138:141], v150 offset:2048
	ds_read_b128 v[150:153], v150 offset:3072
	v_lshl_add_u64 v[184:185], s[68:69], 0, v[180:181]
	s_add_i32 m0, s66, 0xc000
	ds_read_b128 v[154:157], v217
	ds_read_b128 v[158:161], v217 offset:1024
	ds_read_b128 v[170:173], v217 offset:2048
	ds_read_b128 v[206:209], v217 offset:3072
	ds_read_b128 v[210:213], v217 offset:4096
	ds_read_b128 v[218:221], v217 offset:5120
	ds_read_b128 v[236:239], v217 offset:6144
	ds_read_b128 v[240:243], v217 offset:7168
	global_load_lds_dwordx4 v[184:185], off
	s_add_i32 m0, s66, 0xe000
	v_lshl_add_u64 v[184:185], s[68:69], 0, v[182:183]
	global_load_lds_dwordx4 v[184:185], off
	s_waitcnt vmcnt(8)
	s_waitcnt lgkmcnt(0)
	s_barrier
	v_mfma_f32_16x16x32_bf16 v[166:169], v[34:37], v[154:157], v[166:169]
	v_mfma_f32_16x16x32_bf16 v[162:165], v[50:53], v[154:157], v[162:165]
	v_mfma_f32_16x16x32_bf16 v[134:137], v[34:37], v[170:173], v[134:137]
	v_mfma_f32_16x16x32_bf16 v[130:133], v[50:53], v[170:173], v[130:133]
	v_mfma_f32_16x16x32_bf16 v[110:113], v[34:37], v[210:213], v[110:113]
	v_mfma_f32_16x16x32_bf16 v[106:109], v[50:53], v[210:213], v[106:109]
	v_mfma_f32_16x16x32_bf16 v[94:97], v[34:37], v[236:239], v[94:97]
	v_mfma_f32_16x16x32_bf16 v[90:93], v[50:53], v[236:239], v[90:93]
	v_mfma_f32_16x16x32_bf16 v[166:169], v[38:41], v[158:161], v[166:169]
	v_mfma_f32_16x16x32_bf16 v[162:165], v[54:57], v[158:161], v[162:165]
	v_mfma_f32_16x16x32_bf16 v[134:137], v[38:41], v[206:209], v[134:137]
	v_mfma_f32_16x16x32_bf16 v[130:133], v[54:57], v[206:209], v[130:133]
	v_mfma_f32_16x16x32_bf16 v[110:113], v[38:41], v[218:221], v[110:113]
	v_mfma_f32_16x16x32_bf16 v[106:109], v[54:57], v[218:221], v[106:109]
	v_mfma_f32_16x16x32_bf16 v[94:97], v[38:41], v[240:243], v[94:97]
	v_mfma_f32_16x16x32_bf16 v[90:93], v[54:57], v[240:243], v[90:93]
	v_mfma_f32_16x16x32_bf16 v[146:149], v[114:117], v[154:157], v[146:149]
	v_mfma_f32_16x16x32_bf16 v[142:145], v[138:141], v[154:157], v[142:145]
	v_mfma_f32_16x16x32_bf16 v[122:125], v[114:117], v[170:173], v[122:125]
	v_mfma_f32_16x16x32_bf16 v[118:121], v[138:141], v[170:173], v[118:121]
	v_mfma_f32_16x16x32_bf16 v[102:105], v[114:117], v[210:213], v[102:105]
	v_mfma_f32_16x16x32_bf16 v[98:101], v[138:141], v[210:213], v[98:101]
	v_mfma_f32_16x16x32_bf16 v[86:89], v[114:117], v[236:239], v[86:89]
	v_mfma_f32_16x16x32_bf16 v[82:85], v[138:141], v[236:239], v[82:85]
	v_mfma_f32_16x16x32_bf16 v[146:149], v[126:129], v[158:161], v[146:149]
	v_mfma_f32_16x16x32_bf16 v[142:145], v[150:153], v[158:161], v[142:145]
	v_mfma_f32_16x16x32_bf16 v[122:125], v[126:129], v[206:209], v[122:125]
	v_mfma_f32_16x16x32_bf16 v[118:121], v[150:153], v[206:209], v[118:121]
	v_mfma_f32_16x16x32_bf16 v[102:105], v[126:129], v[218:221], v[102:105]
	v_mfma_f32_16x16x32_bf16 v[98:101], v[150:153], v[218:221], v[98:101]
	v_mfma_f32_16x16x32_bf16 v[86:89], v[126:129], v[240:243], v[86:89]
	v_mfma_f32_16x16x32_bf16 v[82:85], v[150:153], v[240:243], v[82:85]
	s_barrier
	s_add_i32 s10, s11, s25
	v_lshl_add_u64 v[184:185], s[72:73], 0, v[190:191]
	s_mov_b32 m0, s10
	ds_read_b128 v[154:157], v217 offset:16384
	ds_read_b128 v[158:161], v217 offset:17408
	ds_read_b128 v[170:173], v217 offset:18432
	ds_read_b128 v[206:209], v217 offset:19456
	ds_read_b128 v[210:213], v217 offset:20480
	ds_read_b128 v[218:221], v217 offset:21504
	ds_read_b128 v[236:239], v217 offset:22528
	ds_read_b128 v[240:243], v217 offset:23552
	global_load_lds_dwordx4 v[184:185], off
	s_add_i32 m0, s10, 0x2000
	s_add_u32 s10, s72, 0x8000
	v_lshl_add_u64 v[194:195], s[72:73], 0, v[174:175]
	s_addc_u32 s11, s73, 0
	s_add_i32 s9, s9, s25
	global_load_lds_dwordx4 v[194:195], off
	v_lshl_add_u64 v[196:197], s[10:11], 0, v[190:191]
	s_mov_b32 m0, s9
	v_lshl_add_u64 v[198:199], s[76:77], 0, v[176:177]
	global_load_lds_dwordx4 v[196:197], off
	s_add_i32 m0, s9, 0x2000
	v_lshl_add_u64 v[196:197], s[10:11], 0, v[174:175]
	global_load_lds_dwordx4 v[196:197], off
	s_mov_b32 m0, s66
	v_lshl_add_u64 v[196:197], s[76:77], 0, v[178:179]
	global_load_lds_dwordx4 v[196:197], off
	s_mov_b32 m0, s67
	s_nop 0
	global_load_lds_dwordx4 v[198:199], off
	s_waitcnt vmcnt(8)
	s_waitcnt lgkmcnt(0)
	s_barrier
; #define PG8_STAGE(bufoff, gbase, voff) do { _Pragma("unroll") for (int _i = 0; _i < 2; ++_i) \
;         __builtin_amdgcn_global_load_lds((const unsigned*)((const char*)(gbase) + (voff)[_i]), (PG8_LAS unsigned*)(lds + (bufoff) + ldsw + _i * 8192), 16, 0, 0); } while (0)
; #define PG8_LDA(dst, b, h) do { _Pragma("unroll") for (int m = 0; m < 4; ++m) _Pragma("unroll") for (int k = 0; k < 2; ++k) dst[m][k] = *(const PG8_LAS bf16x8*)(lds + PG8_SA(b, h) + aoff + m * 2048 + k * 1024); } while (0)
; #define PG8_LDB(dst, b, h) do { _Pragma("unroll") for (int n = 0; n < 2; ++n) _Pragma("unroll") for (int k = 0; k < 2; ++k) dst[n][k] = *(const PG8_LAS bf16x8*)(lds + PG8_SB(b, h) + boff + n * 2048 + k * 1024); } while (0)
; #define PG8_MMA(ai, bj, At, Bt) do { __builtin_amdgcn_s_setprio(1); _Pragma("unroll") for (int m = 0; m < 4; ++m) _Pragma("unroll") for (int n = 0; n < 2; ++n) _Pragma("unroll") for (int k = 0; k < 2; ++k) \
;         acc[ai][bj][m][n] = __builtin_amdgcn_mfma_f32_16x16x32_bf16(Bt[n][k], At[m][k], acc[ai][bj][m][n], 0, 0, 0); __builtin_amdgcn_s_setprio(0); } while (0)
; #define PG8_WAIT_V(n) asm volatile("s_waitcnt vmcnt(" #n ")" ::: "memory")
; #define PG8_WAIT_L(n) asm volatile("s_waitcnt lgkmcnt(" #n ")" ::: "memory")
; #define PG8_BAR __builtin_amdgcn_s_barrier()
; #define PG8_SCHED __builtin_amdgcn_sched_barrier(0)
; template <class Epi, class Sched, bool ALIGN_EPI = false, bool SP2 = false>
; __device__ __forceinline__ void gemm_phase(PG8_LAS unsigned char* lds, const Gemm g, const Sched& S, const Epi& E) {
;     ...
;             PG8_WAIT_V(8); PG8_WAIT_L(0); PG8_BAR; PG8_MMA(1, 0, At, B0); PG8_MMA(1, 1, At, B1); PG8_BAR; PG8_SCHED;
;             PG8_LDB(B0, 1, 0); PG8_LDB(B1, 1, 1); PG8_SCHED; PG8_LDA(At, 1, 0); PG8_STAGE(PG8_SA(0, 1), a2 + hstep, voffA);
;             PG8_WAIT_V(8); PG8_WAIT_L(0); PG8_BAR; PG8_MMA(0, 0, At, B0); PG8_MMA(0, 1, At, B1); PG8_BAR; PG8_SCHED;
	v_mfma_f32_16x16x32_bf16 v[78:81], v[34:37], v[154:157], v[78:81]
	v_mfma_f32_16x16x32_bf16 v[74:77], v[50:53], v[154:157], v[74:77]
	v_mfma_f32_16x16x32_bf16 v[62:65], v[34:37], v[170:173], v[62:65]
	v_mfma_f32_16x16x32_bf16 v[58:61], v[50:53], v[170:173], v[58:61]
	v_mfma_f32_16x16x32_bf16 v[30:33], v[34:37], v[210:213], v[30:33]
	v_mfma_f32_16x16x32_bf16 v[26:29], v[50:53], v[210:213], v[26:29]
	v_mfma_f32_16x16x32_bf16 v[14:17], v[34:37], v[236:239], v[14:17]
	v_mfma_f32_16x16x32_bf16 v[10:13], v[50:53], v[236:239], v[10:13]
	v_mfma_f32_16x16x32_bf16 v[78:81], v[38:41], v[158:161], v[78:81]
	v_mfma_f32_16x16x32_bf16 v[74:77], v[54:57], v[158:161], v[74:77]
	v_mfma_f32_16x16x32_bf16 v[62:65], v[38:41], v[206:209], v[62:65]
	v_mfma_f32_16x16x32_bf16 v[58:61], v[54:57], v[206:209], v[58:61]
	v_mfma_f32_16x16x32_bf16 v[30:33], v[38:41], v[218:221], v[30:33]
	v_mfma_f32_16x16x32_bf16 v[26:29], v[54:57], v[218:221], v[26:29]
	v_mfma_f32_16x16x32_bf16 v[14:17], v[38:41], v[240:243], v[14:17]
	v_mfma_f32_16x16x32_bf16 v[10:13], v[54:57], v[240:243], v[10:13]
	v_mfma_f32_16x16x32_bf16 v[46:49], v[114:117], v[170:173], v[46:49]
	v_mfma_f32_16x16x32_bf16 v[42:45], v[138:141], v[170:173], v[42:45]
	v_mfma_f32_16x16x32_bf16 v[22:25], v[114:117], v[210:213], v[22:25]
	v_mfma_f32_16x16x32_bf16 v[18:21], v[138:141], v[210:213], v[18:21]
	v_mfma_f32_16x16x32_bf16 v[6:9], v[114:117], v[236:239], v[6:9]
	v_mfma_f32_16x16x32_bf16 v[2:5], v[138:141], v[236:239], v[2:5]
	v_mfma_f32_16x16x32_bf16 v[34:37], v[114:117], v[154:157], v[70:73]
	v_mfma_f32_16x16x32_bf16 v[38:41], v[138:141], v[154:157], v[66:69]
	v_mfma_f32_16x16x32_bf16 v[46:49], v[126:129], v[206:209], v[46:49]
	v_mfma_f32_16x16x32_bf16 v[42:45], v[150:153], v[206:209], v[42:45]
	v_mfma_f32_16x16x32_bf16 v[22:25], v[126:129], v[218:221], v[22:25]
	v_mfma_f32_16x16x32_bf16 v[18:21], v[150:153], v[218:221], v[18:21]
	v_mfma_f32_16x16x32_bf16 v[6:9], v[126:129], v[240:243], v[6:9]
	v_mfma_f32_16x16x32_bf16 v[2:5], v[150:153], v[240:243], v[2:5]
	v_mfma_f32_16x16x32_bf16 v[34:37], v[126:129], v[158:161], v[34:37]
	v_mfma_f32_16x16x32_bf16 v[38:41], v[150:153], v[158:161], v[38:41]
	s_barrier
	s_add_i32 s9, 0, 0x18000
	s_add_i32 s12, 0, 0x1c000
	v_add_u32_e32 v70, s9, v193
	v_add_u32_e32 v150, s12, v193
	ds_read_b128 v[50:53], v70
	ds_read_b128 v[54:57], v70 offset:1024
	ds_read_b128 v[66:69], v70 offset:2048
	ds_read_b128 v[70:73], v70 offset:3072
	ds_read_b128 v[114:117], v150
	ds_read_b128 v[126:129], v150 offset:1024
	ds_read_b128 v[138:141], v150 offset:2048
	ds_read_b128 v[150:153], v150 offset:3072
	s_add_u32 s10, s76, 0x20000
	s_addc_u32 s11, s77, 0
	s_mov_b32 m0, s80
	v_lshl_add_u64 v[214:215], s[10:11], 0, v[178:179]
	ds_read_b128 v[154:157], v217 offset:32768
	ds_read_b128 v[158:161], v217 offset:33792
	ds_read_b128 v[170:173], v217 offset:34816
	ds_read_b128 v[206:209], v217 offset:35840
	ds_read_b128 v[210:213], v217 offset:36864
	ds_read_b128 v[218:221], v217 offset:37888
	ds_read_b128 v[236:239], v217 offset:38912
	ds_read_b128 v[240:243], v217 offset:39936
	global_load_lds_dwordx4 v[214:215], off
	s_mov_b32 m0, s81
	v_lshl_add_u64 v[214:215], s[10:11], 0, v[176:177]
	global_load_lds_dwordx4 v[214:215], off
	s_waitcnt vmcnt(8)
	s_waitcnt lgkmcnt(0)
	s_barrier
	v_mfma_f32_16x16x32_bf16 v[166:169], v[50:53], v[154:157], v[166:169]
	v_mfma_f32_16x16x32_bf16 v[162:165], v[66:69], v[154:157], v[162:165]
	v_mfma_f32_16x16x32_bf16 v[134:137], v[50:53], v[170:173], v[134:137]
	v_mfma_f32_16x16x32_bf16 v[130:133], v[66:69], v[170:173], v[130:133]
	v_mfma_f32_16x16x32_bf16 v[110:113], v[50:53], v[210:213], v[110:113]
	v_mfma_f32_16x16x32_bf16 v[106:109], v[66:69], v[210:213], v[106:109]
	v_mfma_f32_16x16x32_bf16 v[94:97], v[50:53], v[236:239], v[94:97]
	v_mfma_f32_16x16x32_bf16 v[90:93], v[66:69], v[236:239], v[90:93]
	v_mfma_f32_16x16x32_bf16 v[166:169], v[54:57], v[158:161], v[166:169]
	v_mfma_f32_16x16x32_bf16 v[162:165], v[70:73], v[158:161], v[162:165]
	v_mfma_f32_16x16x32_bf16 v[134:137], v[54:57], v[206:209], v[134:137]
	v_mfma_f32_16x16x32_bf16 v[130:133], v[70:73], v[206:209], v[130:133]
	v_mfma_f32_16x16x32_bf16 v[110:113], v[54:57], v[218:221], v[110:113]
	v_mfma_f32_16x16x32_bf16 v[106:109], v[70:73], v[218:221], v[106:109]
	v_mfma_f32_16x16x32_bf16 v[94:97], v[54:57], v[240:243], v[94:97]
	v_mfma_f32_16x16x32_bf16 v[90:93], v[70:73], v[240:243], v[90:93]
	v_mfma_f32_16x16x32_bf16 v[146:149], v[114:117], v[154:157], v[146:149]
	v_mfma_f32_16x16x32_bf16 v[142:145], v[138:141], v[154:157], v[142:145]
	v_mfma_f32_16x16x32_bf16 v[122:125], v[114:117], v[170:173], v[122:125]
	v_mfma_f32_16x16x32_bf16 v[118:121], v[138:141], v[170:173], v[118:121]
	v_mfma_f32_16x16x32_bf16 v[102:105], v[114:117], v[210:213], v[102:105]
	v_mfma_f32_16x16x32_bf16 v[98:101], v[138:141], v[210:213], v[98:101]
	v_mfma_f32_16x16x32_bf16 v[86:89], v[114:117], v[236:239], v[86:89]
	v_mfma_f32_16x16x32_bf16 v[82:85], v[138:141], v[236:239], v[82:85]
	v_mfma_f32_16x16x32_bf16 v[146:149], v[126:129], v[158:161], v[146:149]
	v_mfma_f32_16x16x32_bf16 v[142:145], v[150:153], v[158:161], v[142:145]
	v_mfma_f32_16x16x32_bf16 v[122:125], v[126:129], v[206:209], v[122:125]
	v_mfma_f32_16x16x32_bf16 v[118:121], v[150:153], v[206:209], v[118:121]
	v_mfma_f32_16x16x32_bf16 v[102:105], v[126:129], v[218:221], v[102:105]
	v_mfma_f32_16x16x32_bf16 v[98:101], v[150:153], v[218:221], v[98:101]
	v_mfma_f32_16x16x32_bf16 v[86:89], v[126:129], v[240:243], v[86:89]
	v_mfma_f32_16x16x32_bf16 v[82:85], v[150:153], v[240:243], v[82:85]
	s_barrier
; #define PG8_STAGE(bufoff, gbase, voff) do { _Pragma("unroll") for (int _i = 0; _i < 2; ++_i) \
;         __builtin_amdgcn_global_load_lds((const unsigned*)((const char*)(gbase) + (voff)[_i]), (PG8_LAS unsigned*)(lds + (bufoff) + ldsw + _i * 8192), 16, 0, 0); } while (0)
; #define PG8_LDA(dst, b, h) do { _Pragma("unroll") for (int m = 0; m < 4; ++m) _Pragma("unroll") for (int k = 0; k < 2; ++k) dst[m][k] = *(const PG8_LAS bf16x8*)(lds + PG8_SA(b, h) + aoff + m * 2048 + k * 1024); } while (0)
; #define PG8_MMA(ai, bj, At, Bt) do { __builtin_amdgcn_s_setprio(1); _Pragma("unroll") for (int m = 0; m < 4; ++m) _Pragma("unroll") for (int n = 0; n < 2; ++n) _Pragma("unroll") for (int k = 0; k < 2; ++k) \
;         acc[ai][bj][m][n] = __builtin_amdgcn_mfma_f32_16x16x32_bf16(Bt[n][k], At[m][k], acc[ai][bj][m][n], 0, 0, 0); __builtin_amdgcn_s_setprio(0); } while (0)
; #define PG8_WAIT_V(n) asm volatile("s_waitcnt vmcnt(" #n ")" ::: "memory")
; #define PG8_WAIT_L(n) asm volatile("s_waitcnt lgkmcnt(" #n ")" ::: "memory")
; #define PG8_BAR __builtin_amdgcn_s_barrier()
; #define PG8_SCHED __builtin_amdgcn_sched_barrier(0)
; template <class Epi, class Sched, bool ALIGN_EPI = false, bool SP2 = false>
; __device__ __forceinline__ void gemm_phase(PG8_LAS unsigned char* lds, const Gemm g, const Sched& S, const Epi& E) {
;     ...
;             PG8_LDA(At, 1, 1); PG8_STAGE(PG8_SB(1, 0), b3, voffB); PG8_STAGE(PG8_SB(1, 1), b3 + hstepB, voffB); PG8_STAGE(PG8_SA(1, 0), a3, voffA);
;             PG8_WAIT_V(8); PG8_WAIT_L(0); PG8_BAR; PG8_MMA(1, 0, At, B0); PG8_MMA(1, 1, At, B1); PG8_BAR; PG8_SCHED;
	s_add_i32 s9, s9, s25
	v_lshl_add_u64 v[184:185], v[184:185], 0, s[60:61]
	s_mov_b32 m0, s9
	ds_read_b128 v[154:157], v217 offset:49152
	ds_read_b128 v[158:161], v217 offset:50176
	ds_read_b128 v[170:173], v217 offset:51200
	ds_read_b128 v[206:209], v217 offset:52224
	ds_read_b128 v[210:213], v217 offset:53248
	ds_read_b128 v[218:221], v217 offset:54272
	ds_read_b128 v[236:239], v217 offset:55296
	ds_read_b128 v[240:243], v217 offset:56320
	global_load_lds_dwordx4 v[184:185], off
	s_add_i32 m0, s9, 0x2000
	s_add_u32 s10, s72, 0x8080
	v_lshl_add_u64 v[184:185], v[194:195], 0, s[60:61]
	s_addc_u32 s11, s73, 0
	s_add_i32 s9, s12, s25
	global_load_lds_dwordx4 v[184:185], off
	s_mov_b32 m0, s9
	v_lshl_add_u64 v[184:185], s[10:11], 0, v[190:191]
	global_load_lds_dwordx4 v[184:185], off
	s_add_i32 m0, s9, 0x2000
	v_lshl_add_u64 v[184:185], s[10:11], 0, v[174:175]
	global_load_lds_dwordx4 v[184:185], off
	s_mov_b32 m0, s82
	v_lshl_add_u64 v[184:185], v[196:197], 0, s[60:61]
	global_load_lds_dwordx4 v[184:185], off
	s_mov_b32 m0, s92
	v_lshl_add_u64 v[184:185], v[198:199], 0, s[60:61]
	global_load_lds_dwordx4 v[184:185], off
	s_waitcnt vmcnt(8)
	s_waitcnt lgkmcnt(0)
	s_barrier
	v_mfma_f32_16x16x32_bf16 v[78:81], v[50:53], v[154:157], v[78:81]
	v_mfma_f32_16x16x32_bf16 v[74:77], v[66:69], v[154:157], v[74:77]
	v_mfma_f32_16x16x32_bf16 v[62:65], v[50:53], v[170:173], v[62:65]
	v_mfma_f32_16x16x32_bf16 v[58:61], v[66:69], v[170:173], v[58:61]
	v_mfma_f32_16x16x32_bf16 v[30:33], v[50:53], v[210:213], v[30:33]
	v_mfma_f32_16x16x32_bf16 v[26:29], v[66:69], v[210:213], v[26:29]
	v_mfma_f32_16x16x32_bf16 v[14:17], v[50:53], v[236:239], v[14:17]
	v_mfma_f32_16x16x32_bf16 v[10:13], v[66:69], v[236:239], v[10:13]
	v_mfma_f32_16x16x32_bf16 v[78:81], v[54:57], v[158:161], v[78:81]
	v_mfma_f32_16x16x32_bf16 v[74:77], v[70:73], v[158:161], v[74:77]
	v_mfma_f32_16x16x32_bf16 v[62:65], v[54:57], v[206:209], v[62:65]
	v_mfma_f32_16x16x32_bf16 v[58:61], v[70:73], v[206:209], v[58:61]
	v_mfma_f32_16x16x32_bf16 v[30:33], v[54:57], v[218:221], v[30:33]
	v_mfma_f32_16x16x32_bf16 v[26:29], v[70:73], v[218:221], v[26:29]
	v_mfma_f32_16x16x32_bf16 v[14:17], v[54:57], v[240:243], v[14:17]
	v_mfma_f32_16x16x32_bf16 v[10:13], v[70:73], v[240:243], v[10:13]
	v_mfma_f32_16x16x32_bf16 v[34:37], v[114:117], v[154:157], v[34:37]
	v_mfma_f32_16x16x32_bf16 v[70:73], v[126:129], v[158:161], v[34:37]
	v_mfma_f32_16x16x32_bf16 v[34:37], v[138:141], v[154:157], v[38:41]
	v_mfma_f32_16x16x32_bf16 v[66:69], v[150:153], v[158:161], v[34:37]
	v_mfma_f32_16x16x32_bf16 v[34:37], v[114:117], v[170:173], v[46:49]
	v_mfma_f32_16x16x32_bf16 v[46:49], v[126:129], v[206:209], v[34:37]
	v_mfma_f32_16x16x32_bf16 v[34:37], v[138:141], v[170:173], v[42:45]
	v_mfma_f32_16x16x32_bf16 v[22:25], v[114:117], v[210:213], v[22:25]
	v_mfma_f32_16x16x32_bf16 v[18:21], v[138:141], v[210:213], v[18:21]
	v_mfma_f32_16x16x32_bf16 v[6:9], v[114:117], v[236:239], v[6:9]
	v_mfma_f32_16x16x32_bf16 v[2:5], v[138:141], v[236:239], v[2:5]
	v_mfma_f32_16x16x32_bf16 v[42:45], v[150:153], v[206:209], v[34:37]
	v_mfma_f32_16x16x32_bf16 v[22:25], v[126:129], v[218:221], v[22:25]
	v_mfma_f32_16x16x32_bf16 v[18:21], v[150:153], v[218:221], v[18:21]
	v_mfma_f32_16x16x32_bf16 v[6:9], v[126:129], v[240:243], v[6:9]
	v_mfma_f32_16x16x32_bf16 v[2:5], v[150:153], v[240:243], v[2:5]
	s_barrier
	s_add_i32 s8, s8, 2
	s_add_u32 s68, s68, 0x100
	s_addc_u32 s69, s69, 0
	s_add_u32 s6, s6, 0x100
	s_addc_u32 s7, s7, 0
	s_cmp_gt_u32 s8, 5
	s_cbranch_scc0 .LBB0_788
	s_and_b64 vcc, exec, s[46:47]
	s_cbranch_vccz .LBB0_791
	s_barrier

; #define PG8_STAGE(bufoff, gbase, voff) do { _Pragma("unroll") for (int _i = 0; _i < 2; ++_i) \
;         __builtin_amdgcn_global_load_lds((const unsigned*)((const char*)(gbase) + (voff)[_i]), (PG8_LAS unsigned*)(lds + (bufoff) + ldsw + _i * 8192), 16, 0, 0); } while (0)
; #define PG8_LDA(dst, b, h) do { _Pragma("unroll") for (int m = 0; m < 4; ++m) _Pragma("unroll") for (int k = 0; k < 2; ++k) dst[m][k] = *(const PG8_LAS bf16x8*)(lds + PG8_SA(b, h) + aoff + m * 2048 + k * 1024); } while (0)
; #define PG8_LDB(dst, b, h) do { _Pragma("unroll") for (int n = 0; n < 2; ++n) _Pragma("unroll") for (int k = 0; k < 2; ++k) dst[n][k] = *(const PG8_LAS bf16x8*)(lds + PG8_SB(b, h) + boff + n * 2048 + k * 1024); } while (0)
; #define PG8_MMA(ai, bj, At, Bt) do { __builtin_amdgcn_s_setprio(1); _Pragma("unroll") for (int m = 0; m < 4; ++m) _Pragma("unroll") for (int n = 0; n < 2; ++n) _Pragma("unroll") for (int k = 0; k < 2; ++k) \
;         acc[ai][bj][m][n] = __builtin_amdgcn_mfma_f32_16x16x32_bf16(Bt[n][k], At[m][k], acc[ai][bj][m][n], 0, 0, 0); __builtin_amdgcn_s_setprio(0); } while (0)
; #define PG8_WAIT_V(n) asm volatile("s_waitcnt vmcnt(" #n ")" ::: "memory")
; #define PG8_WAIT_L(n) asm volatile("s_waitcnt lgkmcnt(" #n ")" ::: "memory")
; #define PG8_BAR __builtin_amdgcn_s_barrier()
; template <class Epi, class Sched, bool ALIGN_EPI = false, bool SP2 = false>
; __device__ __forceinline__ void gemm_phase(PG8_LAS unsigned char* lds, const Gemm g, const Sched& S, const Epi& E) {
;     ...
;             const char* a1 = cA + (size_t)(t + 1) * kstep;
;             const char* a2 = last ? nA : cA + (size_t)(t + 2) * kstep; const char* b2 = last ? nB : cB + (size_t)(t + 2) * kstep;
;             const char* a3 = a2 + kstep; const char* b3 = b2 + kstep;
;             if (last && has_next) S.a_ready(nxt);
;             if constexpr (SP2) {
;             PG8_LDB(B0, 0, 0); PG8_LDB(B1, 0, 1); PG8_SCHED; PG8_LDA(At, 0, 0); PG8_STAGE(PG8_SA(1, 1), a1 + hstep, voffA);
;             PG8_WAIT_V(8); PG8_WAIT_L(0); PG8_BAR; PG8_MMA(0, 0, At, B0); PG8_MMA(0, 1, At, B1); PG8_BAR; PG8_SCHED;
;             PG8_LDA(At, 0, 1); PG8_STAGE(PG8_SB(0, 0), b2, voffB); PG8_STAGE(PG8_SB(0, 1), b2 + hstepB, voffB); PG8_STAGE(PG8_SA(0, 0), a2, voffA);
;             PG8_WAIT_V(8); PG8_WAIT_L(0); PG8_BAR; PG8_MMA(1, 0, At, B0); PG8_MMA(1, 1, At, B1); PG8_BAR; PG8_SCHED;
.LBB0_927:
	s_add_u32 s9, s38, 0xfff80080
	s_addc_u32 s10, s39, -1
	s_add_i32 s11, 0, 0x10000
	s_cmp_eq_u32 s8, 28
	s_cselect_b32 s95, s36, s10
	s_cselect_b32 s94, s37, s9
	s_cselect_b32 s47, s4, s7
	s_cselect_b32 s46, s5, s6
	s_add_i32 s9, 0, 0x14000
	v_add_u32_e32 v86, s11, v193
	v_add_u32_e32 v158, s9, v193
	ds_read_b128 v[66:69], v86
	ds_read_b128 v[70:73], v86 offset:1024
	ds_read_b128 v[78:81], v86 offset:2048
	ds_read_b128 v[86:89], v86 offset:3072
	ds_read_b128 v[146:149], v158
	ds_read_b128 v[150:153], v158 offset:1024
	ds_read_b128 v[154:157], v158 offset:2048
	ds_read_b128 v[158:161], v158 offset:3072
	v_lshl_add_u64 v[194:195], s[38:39], 0, v[212:213]
	s_add_i32 m0, s66, 0xc000
	ds_read_b128 v[162:165], v236
	ds_read_b128 v[166:169], v236 offset:1024
	ds_read_b128 v[170:173], v236 offset:2048
	ds_read_b128 v[174:177], v236 offset:3072
	ds_read_b128 v[178:181], v236 offset:4096
	ds_read_b128 v[182:185], v236 offset:5120
	ds_read_b128 v[216:219], v236 offset:6144
	ds_read_b128 v[220:223], v236 offset:7168
	global_load_lds_dwordx4 v[194:195], off
	s_add_i32 m0, s66, 0xe000
	v_lshl_add_u64 v[194:195], s[38:39], 0, v[214:215]
	global_load_lds_dwordx4 v[194:195], off
	s_waitcnt vmcnt(8)
	s_waitcnt lgkmcnt(0)
	s_barrier
	v_mfma_f32_16x16x32_bf16 v[142:145], v[66:69], v[162:165], v[142:145]
	v_mfma_f32_16x16x32_bf16 v[138:141], v[78:81], v[162:165], v[138:141]
	v_mfma_f32_16x16x32_bf16 v[126:129], v[66:69], v[170:173], v[126:129]
	v_mfma_f32_16x16x32_bf16 v[122:125], v[78:81], v[170:173], v[122:125]
	v_mfma_f32_16x16x32_bf16 v[110:113], v[66:69], v[178:181], v[110:113]
	v_mfma_f32_16x16x32_bf16 v[106:109], v[78:81], v[178:181], v[106:109]
	v_mfma_f32_16x16x32_bf16 v[94:97], v[66:69], v[216:219], v[94:97]
	v_mfma_f32_16x16x32_bf16 v[90:93], v[78:81], v[216:219], v[90:93]
	v_mfma_f32_16x16x32_bf16 v[142:145], v[70:73], v[166:169], v[142:145]
	v_mfma_f32_16x16x32_bf16 v[138:141], v[86:89], v[166:169], v[138:141]
	v_mfma_f32_16x16x32_bf16 v[126:129], v[70:73], v[174:177], v[126:129]
	v_mfma_f32_16x16x32_bf16 v[122:125], v[86:89], v[174:177], v[122:125]
	v_mfma_f32_16x16x32_bf16 v[110:113], v[70:73], v[182:185], v[110:113]
	v_mfma_f32_16x16x32_bf16 v[106:109], v[86:89], v[182:185], v[106:109]
	v_mfma_f32_16x16x32_bf16 v[94:97], v[70:73], v[220:223], v[94:97]
	v_mfma_f32_16x16x32_bf16 v[90:93], v[86:89], v[220:223], v[90:93]
	v_mfma_f32_16x16x32_bf16 v[134:137], v[146:149], v[162:165], v[134:137]
	v_mfma_f32_16x16x32_bf16 v[130:133], v[154:157], v[162:165], v[130:133]
	v_mfma_f32_16x16x32_bf16 v[118:121], v[146:149], v[170:173], v[118:121]
	v_mfma_f32_16x16x32_bf16 v[114:117], v[154:157], v[170:173], v[114:117]
	v_mfma_f32_16x16x32_bf16 v[102:105], v[146:149], v[178:181], v[102:105]
	v_mfma_f32_16x16x32_bf16 v[98:101], v[154:157], v[178:181], v[98:101]
	v_mfma_f32_16x16x32_bf16 v[82:85], v[146:149], v[216:219], v[82:85]
	v_mfma_f32_16x16x32_bf16 v[74:77], v[154:157], v[216:219], v[74:77]
	v_mfma_f32_16x16x32_bf16 v[134:137], v[150:153], v[166:169], v[134:137]
	v_mfma_f32_16x16x32_bf16 v[130:133], v[158:161], v[166:169], v[130:133]
	v_mfma_f32_16x16x32_bf16 v[118:121], v[150:153], v[174:177], v[118:121]
	v_mfma_f32_16x16x32_bf16 v[114:117], v[158:161], v[174:177], v[114:117]
	v_mfma_f32_16x16x32_bf16 v[102:105], v[150:153], v[182:185], v[102:105]
	v_mfma_f32_16x16x32_bf16 v[98:101], v[158:161], v[182:185], v[98:101]
	v_mfma_f32_16x16x32_bf16 v[82:85], v[150:153], v[220:223], v[82:85]
	v_mfma_f32_16x16x32_bf16 v[74:77], v[158:161], v[220:223], v[74:77]
	s_barrier
	s_add_i32 s10, s11, s25
	v_lshl_add_u64 v[194:195], s[46:47], 0, v[190:191]
	s_mov_b32 m0, s10
	ds_read_b128 v[162:165], v236 offset:16384
	ds_read_b128 v[166:169], v236 offset:17408
	ds_read_b128 v[170:173], v236 offset:18432
	ds_read_b128 v[174:177], v236 offset:19456
	ds_read_b128 v[178:181], v236 offset:20480
	ds_read_b128 v[182:185], v236 offset:21504
	ds_read_b128 v[216:219], v236 offset:22528
	ds_read_b128 v[220:223], v236 offset:23552
	global_load_lds_dwordx4 v[194:195], off
	s_add_i32 m0, s10, 0x2000
	s_add_u32 s10, s46, 0x20000
	v_lshl_add_u64 v[196:197], s[46:47], 0, v[206:207]
	s_addc_u32 s11, s47, 0
	s_add_i32 s9, s9, s25
	global_load_lds_dwordx4 v[196:197], off
	v_lshl_add_u64 v[198:199], s[10:11], 0, v[190:191]
	s_mov_b32 m0, s9
	v_lshl_add_u64 v[238:239], s[94:95], 0, v[208:209]
	global_load_lds_dwordx4 v[198:199], off
	s_add_i32 m0, s9, 0x2000
	v_lshl_add_u64 v[198:199], s[10:11], 0, v[206:207]
	global_load_lds_dwordx4 v[198:199], off
	s_mov_b32 m0, s66
	v_lshl_add_u64 v[198:199], s[94:95], 0, v[210:211]
	global_load_lds_dwordx4 v[198:199], off
	s_mov_b32 m0, s67
	s_nop 0
	global_load_lds_dwordx4 v[238:239], off
	s_waitcnt vmcnt(8)
	s_waitcnt lgkmcnt(0)
	s_barrier
; #define PG8_STAGE(bufoff, gbase, voff) do { _Pragma("unroll") for (int _i = 0; _i < 2; ++_i) \
;         __builtin_amdgcn_global_load_lds((const unsigned*)((const char*)(gbase) + (voff)[_i]), (PG8_LAS unsigned*)(lds + (bufoff) + ldsw + _i * 8192), 16, 0, 0); } while (0)
; #define PG8_LDA(dst, b, h) do { _Pragma("unroll") for (int m = 0; m < 4; ++m) _Pragma("unroll") for (int k = 0; k < 2; ++k) dst[m][k] = *(const PG8_LAS bf16x8*)(lds + PG8_SA(b, h) + aoff + m * 2048 + k * 1024); } while (0)
; #define PG8_LDB(dst, b, h) do { _Pragma("unroll") for (int n = 0; n < 2; ++n) _Pragma("unroll") for (int k = 0; k < 2; ++k) dst[n][k] = *(const PG8_LAS bf16x8*)(lds + PG8_SB(b, h) + boff + n * 2048 + k * 1024); } while (0)
; #define PG8_MMA(ai, bj, At, Bt) do { __builtin_amdgcn_s_setprio(1); _Pragma("unroll") for (int m = 0; m < 4; ++m) _Pragma("unroll") for (int n = 0; n < 2; ++n) _Pragma("unroll") for (int k = 0; k < 2; ++k) \
;         acc[ai][bj][m][n] = __builtin_amdgcn_mfma_f32_16x16x32_bf16(Bt[n][k], At[m][k], acc[ai][bj][m][n], 0, 0, 0); __builtin_amdgcn_s_setprio(0); } while (0)
; #define PG8_WAIT_V(n) asm volatile("s_waitcnt vmcnt(" #n ")" ::: "memory")
; #define PG8_WAIT_L(n) asm volatile("s_waitcnt lgkmcnt(" #n ")" ::: "memory")
; #define PG8_BAR __builtin_amdgcn_s_barrier()
; #define PG8_SCHED __builtin_amdgcn_sched_barrier(0)
; template <class Epi, class Sched, bool ALIGN_EPI = false, bool SP2 = false>
; __device__ __forceinline__ void gemm_phase(PG8_LAS unsigned char* lds, const Gemm g, const Sched& S, const Epi& E) {
;     ...
;             PG8_WAIT_V(8); PG8_WAIT_L(0); PG8_BAR; PG8_MMA(1, 0, At, B0); PG8_MMA(1, 1, At, B1); PG8_BAR; PG8_SCHED;
;             PG8_LDB(B0, 1, 0); PG8_LDB(B1, 1, 1); PG8_SCHED; PG8_LDA(At, 1, 0); PG8_STAGE(PG8_SA(0, 1), a2 + hstep, voffA);
;             PG8_WAIT_V(8); PG8_WAIT_L(0); PG8_BAR; PG8_MMA(0, 0, At, B0); PG8_MMA(0, 1, At, B1); PG8_BAR; PG8_SCHED;
	v_mfma_f32_16x16x32_bf16 v[62:65], v[66:69], v[162:165], v[62:65]
	v_mfma_f32_16x16x32_bf16 v[58:61], v[78:81], v[162:165], v[58:61]
	v_mfma_f32_16x16x32_bf16 v[46:49], v[66:69], v[170:173], v[46:49]
	v_mfma_f32_16x16x32_bf16 v[42:45], v[78:81], v[170:173], v[42:45]
	v_mfma_f32_16x16x32_bf16 v[30:33], v[66:69], v[178:181], v[30:33]
	v_mfma_f32_16x16x32_bf16 v[26:29], v[78:81], v[178:181], v[26:29]
	v_mfma_f32_16x16x32_bf16 v[14:17], v[66:69], v[216:219], v[14:17]
	v_mfma_f32_16x16x32_bf16 v[10:13], v[78:81], v[216:219], v[10:13]
	v_mfma_f32_16x16x32_bf16 v[62:65], v[70:73], v[166:169], v[62:65]
	v_mfma_f32_16x16x32_bf16 v[58:61], v[86:89], v[166:169], v[58:61]
	v_mfma_f32_16x16x32_bf16 v[46:49], v[70:73], v[174:177], v[46:49]
	v_mfma_f32_16x16x32_bf16 v[42:45], v[86:89], v[174:177], v[42:45]
	v_mfma_f32_16x16x32_bf16 v[30:33], v[70:73], v[182:185], v[30:33]
	v_mfma_f32_16x16x32_bf16 v[26:29], v[86:89], v[182:185], v[26:29]
	v_mfma_f32_16x16x32_bf16 v[14:17], v[70:73], v[220:223], v[14:17]
	v_mfma_f32_16x16x32_bf16 v[10:13], v[86:89], v[220:223], v[10:13]
	v_mfma_f32_16x16x32_bf16 v[54:57], v[146:149], v[162:165], v[54:57]
	v_mfma_f32_16x16x32_bf16 v[50:53], v[154:157], v[162:165], v[50:53]
	v_mfma_f32_16x16x32_bf16 v[38:41], v[146:149], v[170:173], v[38:41]
	v_mfma_f32_16x16x32_bf16 v[34:37], v[154:157], v[170:173], v[34:37]
	v_mfma_f32_16x16x32_bf16 v[22:25], v[146:149], v[178:181], v[22:25]
	v_mfma_f32_16x16x32_bf16 v[18:21], v[154:157], v[178:181], v[18:21]
	v_mfma_f32_16x16x32_bf16 v[6:9], v[146:149], v[216:219], v[6:9]
	v_mfma_f32_16x16x32_bf16 v[2:5], v[154:157], v[216:219], v[2:5]
	v_mfma_f32_16x16x32_bf16 v[54:57], v[150:153], v[166:169], v[54:57]
	v_mfma_f32_16x16x32_bf16 v[50:53], v[158:161], v[166:169], v[50:53]
	v_mfma_f32_16x16x32_bf16 v[38:41], v[150:153], v[174:177], v[38:41]
	v_mfma_f32_16x16x32_bf16 v[34:37], v[158:161], v[174:177], v[34:37]
	v_mfma_f32_16x16x32_bf16 v[22:25], v[150:153], v[182:185], v[22:25]
	v_mfma_f32_16x16x32_bf16 v[18:21], v[158:161], v[182:185], v[18:21]
	v_mfma_f32_16x16x32_bf16 v[6:9], v[150:153], v[220:223], v[6:9]
	v_mfma_f32_16x16x32_bf16 v[2:5], v[158:161], v[220:223], v[2:5]
	s_barrier
	s_add_i32 s9, 0, 0x18000
	s_add_i32 s12, 0, 0x1c000
	v_add_u32_e32 v86, s9, v193
	v_add_u32_e32 v158, s12, v193
	ds_read_b128 v[66:69], v86
	ds_read_b128 v[70:73], v86 offset:1024
	ds_read_b128 v[78:81], v86 offset:2048
	ds_read_b128 v[86:89], v86 offset:3072
	ds_read_b128 v[146:149], v158
	ds_read_b128 v[150:153], v158 offset:1024
	ds_read_b128 v[154:157], v158 offset:2048
	ds_read_b128 v[158:161], v158 offset:3072
	s_add_u32 s10, s94, 0x80000
	s_addc_u32 s11, s95, 0
	s_mov_b32 m0, s59
	v_lshl_add_u64 v[240:241], s[10:11], 0, v[210:211]
	ds_read_b128 v[162:165], v236 offset:32768
	ds_read_b128 v[166:169], v236 offset:33792
	ds_read_b128 v[170:173], v236 offset:34816
	ds_read_b128 v[174:177], v236 offset:35840
	ds_read_b128 v[178:181], v236 offset:36864
	ds_read_b128 v[182:185], v236 offset:37888
	ds_read_b128 v[216:219], v236 offset:38912
	ds_read_b128 v[220:223], v236 offset:39936
	global_load_lds_dwordx4 v[240:241], off
	s_mov_b32 m0, s74
	v_lshl_add_u64 v[240:241], s[10:11], 0, v[208:209]
	global_load_lds_dwordx4 v[240:241], off
	s_waitcnt vmcnt(8)
	s_waitcnt lgkmcnt(0)
	s_barrier
	v_mfma_f32_16x16x32_bf16 v[142:145], v[66:69], v[162:165], v[142:145]
	v_mfma_f32_16x16x32_bf16 v[138:141], v[78:81], v[162:165], v[138:141]
	v_mfma_f32_16x16x32_bf16 v[126:129], v[66:69], v[170:173], v[126:129]
	v_mfma_f32_16x16x32_bf16 v[122:125], v[78:81], v[170:173], v[122:125]
	v_mfma_f32_16x16x32_bf16 v[110:113], v[66:69], v[178:181], v[110:113]
	v_mfma_f32_16x16x32_bf16 v[106:109], v[78:81], v[178:181], v[106:109]
	v_mfma_f32_16x16x32_bf16 v[94:97], v[66:69], v[216:219], v[94:97]
	v_mfma_f32_16x16x32_bf16 v[90:93], v[78:81], v[216:219], v[90:93]
	v_mfma_f32_16x16x32_bf16 v[142:145], v[70:73], v[166:169], v[142:145]
	v_mfma_f32_16x16x32_bf16 v[138:141], v[86:89], v[166:169], v[138:141]
	v_mfma_f32_16x16x32_bf16 v[126:129], v[70:73], v[174:177], v[126:129]
	v_mfma_f32_16x16x32_bf16 v[122:125], v[86:89], v[174:177], v[122:125]
	v_mfma_f32_16x16x32_bf16 v[110:113], v[70:73], v[182:185], v[110:113]
	v_mfma_f32_16x16x32_bf16 v[106:109], v[86:89], v[182:185], v[106:109]
	v_mfma_f32_16x16x32_bf16 v[94:97], v[70:73], v[220:223], v[94:97]
	v_mfma_f32_16x16x32_bf16 v[90:93], v[86:89], v[220:223], v[90:93]
	v_mfma_f32_16x16x32_bf16 v[134:137], v[146:149], v[162:165], v[134:137]
	v_mfma_f32_16x16x32_bf16 v[130:133], v[154:157], v[162:165], v[130:133]
	v_mfma_f32_16x16x32_bf16 v[118:121], v[146:149], v[170:173], v[118:121]
	v_mfma_f32_16x16x32_bf16 v[114:117], v[154:157], v[170:173], v[114:117]
	v_mfma_f32_16x16x32_bf16 v[102:105], v[146:149], v[178:181], v[102:105]
	v_mfma_f32_16x16x32_bf16 v[98:101], v[154:157], v[178:181], v[98:101]
	v_mfma_f32_16x16x32_bf16 v[82:85], v[146:149], v[216:219], v[82:85]
	v_mfma_f32_16x16x32_bf16 v[74:77], v[154:157], v[216:219], v[74:77]
	v_mfma_f32_16x16x32_bf16 v[134:137], v[150:153], v[166:169], v[134:137]
	v_mfma_f32_16x16x32_bf16 v[130:133], v[158:161], v[166:169], v[130:133]
	v_mfma_f32_16x16x32_bf16 v[118:121], v[150:153], v[174:177], v[118:121]
	v_mfma_f32_16x16x32_bf16 v[114:117], v[158:161], v[174:177], v[114:117]
	v_mfma_f32_16x16x32_bf16 v[102:105], v[150:153], v[182:185], v[102:105]
	v_mfma_f32_16x16x32_bf16 v[98:101], v[158:161], v[182:185], v[98:101]
	v_mfma_f32_16x16x32_bf16 v[82:85], v[150:153], v[220:223], v[82:85]
	v_mfma_f32_16x16x32_bf16 v[74:77], v[158:161], v[220:223], v[74:77]
	s_barrier
; #define PG8_STAGE(bufoff, gbase, voff) do { _Pragma("unroll") for (int _i = 0; _i < 2; ++_i) \
;         __builtin_amdgcn_global_load_lds((const unsigned*)((const char*)(gbase) + (voff)[_i]), (PG8_LAS unsigned*)(lds + (bufoff) + ldsw + _i * 8192), 16, 0, 0); } while (0)
; #define PG8_LDA(dst, b, h) do { _Pragma("unroll") for (int m = 0; m < 4; ++m) _Pragma("unroll") for (int k = 0; k < 2; ++k) dst[m][k] = *(const PG8_LAS bf16x8*)(lds + PG8_SA(b, h) + aoff + m * 2048 + k * 1024); } while (0)
; #define PG8_MMA(ai, bj, At, Bt) do { __builtin_amdgcn_s_setprio(1); _Pragma("unroll") for (int m = 0; m < 4; ++m) _Pragma("unroll") for (int n = 0; n < 2; ++n) _Pragma("unroll") for (int k = 0; k < 2; ++k) \
;         acc[ai][bj][m][n] = __builtin_amdgcn_mfma_f32_16x16x32_bf16(Bt[n][k], At[m][k], acc[ai][bj][m][n], 0, 0, 0); __builtin_amdgcn_s_setprio(0); } while (0)
; #define PG8_WAIT_V(n) asm volatile("s_waitcnt vmcnt(" #n ")" ::: "memory")
; #define PG8_WAIT_L(n) asm volatile("s_waitcnt lgkmcnt(" #n ")" ::: "memory")
; #define PG8_BAR __builtin_amdgcn_s_barrier()
; #define PG8_SCHED __builtin_amdgcn_sched_barrier(0)
; template <class Epi, class Sched, bool ALIGN_EPI = false, bool SP2 = false>
; __device__ __forceinline__ void gemm_phase(PG8_LAS unsigned char* lds, const Gemm g, const Sched& S, const Epi& E) {
;     ...
;             PG8_LDA(At, 1, 1); PG8_STAGE(PG8_SB(1, 0), b3, voffB); PG8_STAGE(PG8_SB(1, 1), b3 + hstepB, voffB); PG8_STAGE(PG8_SA(1, 0), a3, voffA);
;             PG8_WAIT_V(8); PG8_WAIT_L(0); PG8_BAR; PG8_MMA(1, 0, At, B0); PG8_MMA(1, 1, At, B1); PG8_BAR; PG8_SCHED;
	s_add_i32 s9, s9, s25
	v_lshl_add_u64 v[194:195], v[194:195], 0, s[60:61]
	s_mov_b32 m0, s9
	ds_read_b128 v[162:165], v236 offset:49152
	ds_read_b128 v[166:169], v236 offset:50176
	ds_read_b128 v[170:173], v236 offset:51200
	ds_read_b128 v[174:177], v236 offset:52224
	ds_read_b128 v[178:181], v236 offset:53248
	ds_read_b128 v[182:185], v236 offset:54272
	ds_read_b128 v[216:219], v236 offset:55296
	ds_read_b128 v[220:223], v236 offset:56320
	global_load_lds_dwordx4 v[194:195], off
	s_add_i32 m0, s9, 0x2000
	s_add_u32 s10, s46, 0x20080
	v_lshl_add_u64 v[194:195], v[196:197], 0, s[60:61]
	s_addc_u32 s11, s47, 0
	s_add_i32 s9, s12, s25
	global_load_lds_dwordx4 v[194:195], off
	s_mov_b32 m0, s9
	v_lshl_add_u64 v[194:195], s[10:11], 0, v[190:191]
	global_load_lds_dwordx4 v[194:195], off
	s_add_i32 m0, s9, 0x2000
	v_lshl_add_u64 v[194:195], s[10:11], 0, v[206:207]
	global_load_lds_dwordx4 v[194:195], off
	s_mov_b32 m0, s75
	v_lshl_add_u64 v[194:195], v[198:199], 0, s[60:61]
	global_load_lds_dwordx4 v[194:195], off
	s_mov_b32 m0, s0
	v_lshl_add_u64 v[194:195], v[238:239], 0, s[60:61]
	global_load_lds_dwordx4 v[194:195], off
	s_waitcnt vmcnt(8)
	s_waitcnt lgkmcnt(0)
	s_barrier
	v_mfma_f32_16x16x32_bf16 v[62:65], v[66:69], v[162:165], v[62:65]
	v_mfma_f32_16x16x32_bf16 v[58:61], v[78:81], v[162:165], v[58:61]
	v_mfma_f32_16x16x32_bf16 v[46:49], v[66:69], v[170:173], v[46:49]
	v_mfma_f32_16x16x32_bf16 v[42:45], v[78:81], v[170:173], v[42:45]
	v_mfma_f32_16x16x32_bf16 v[30:33], v[66:69], v[178:181], v[30:33]
	v_mfma_f32_16x16x32_bf16 v[26:29], v[78:81], v[178:181], v[26:29]
	v_mfma_f32_16x16x32_bf16 v[14:17], v[66:69], v[216:219], v[14:17]
	v_mfma_f32_16x16x32_bf16 v[10:13], v[78:81], v[216:219], v[10:13]
	v_mfma_f32_16x16x32_bf16 v[62:65], v[70:73], v[166:169], v[62:65]
	v_mfma_f32_16x16x32_bf16 v[58:61], v[86:89], v[166:169], v[58:61]
	v_mfma_f32_16x16x32_bf16 v[46:49], v[70:73], v[174:177], v[46:49]
	v_mfma_f32_16x16x32_bf16 v[42:45], v[86:89], v[174:177], v[42:45]
	v_mfma_f32_16x16x32_bf16 v[30:33], v[70:73], v[182:185], v[30:33]
	v_mfma_f32_16x16x32_bf16 v[26:29], v[86:89], v[182:185], v[26:29]
	v_mfma_f32_16x16x32_bf16 v[14:17], v[70:73], v[220:223], v[14:17]
	v_mfma_f32_16x16x32_bf16 v[10:13], v[86:89], v[220:223], v[10:13]
	v_mfma_f32_16x16x32_bf16 v[54:57], v[146:149], v[162:165], v[54:57]
	v_mfma_f32_16x16x32_bf16 v[50:53], v[154:157], v[162:165], v[50:53]
	v_mfma_f32_16x16x32_bf16 v[38:41], v[146:149], v[170:173], v[38:41]
	v_mfma_f32_16x16x32_bf16 v[34:37], v[154:157], v[170:173], v[34:37]
	v_mfma_f32_16x16x32_bf16 v[22:25], v[146:149], v[178:181], v[22:25]
	v_mfma_f32_16x16x32_bf16 v[18:21], v[154:157], v[178:181], v[18:21]
	v_mfma_f32_16x16x32_bf16 v[6:9], v[146:149], v[216:219], v[6:9]
	v_mfma_f32_16x16x32_bf16 v[2:5], v[154:157], v[216:219], v[2:5]
	v_mfma_f32_16x16x32_bf16 v[54:57], v[150:153], v[166:169], v[54:57]
	v_mfma_f32_16x16x32_bf16 v[50:53], v[158:161], v[166:169], v[50:53]
	v_mfma_f32_16x16x32_bf16 v[38:41], v[150:153], v[174:177], v[38:41]
	v_mfma_f32_16x16x32_bf16 v[34:37], v[158:161], v[174:177], v[34:37]
	v_mfma_f32_16x16x32_bf16 v[22:25], v[150:153], v[182:185], v[22:25]
	v_mfma_f32_16x16x32_bf16 v[18:21], v[158:161], v[182:185], v[18:21]
	v_mfma_f32_16x16x32_bf16 v[6:9], v[150:153], v[220:223], v[6:9]
	v_mfma_f32_16x16x32_bf16 v[2:5], v[158:161], v[220:223], v[2:5]
	s_barrier
	s_add_i32 s8, s8, 2
	s_add_u32 s38, s38, 0x100
	s_addc_u32 s39, s39, 0
	s_add_u32 s6, s6, 0x100
	s_addc_u32 s7, s7, 0
	s_cmp_gt_u32 s8, 29
	s_cbranch_scc0 .LBB0_927
	s_and_b64 vcc, exec, s[70:71]
	s_cbranch_vccz .LBB0_930
	s_barrier

; #define PG8_STAGE(bufoff, gbase, voff) do { _Pragma("unroll") for (int _i = 0; _i < 2; ++_i) \
;         __builtin_amdgcn_global_load_lds((const unsigned*)((const char*)(gbase) + (voff)[_i]), (PG8_LAS unsigned*)(lds + (bufoff) + ldsw + _i * 8192), 16, 0, 0); } while (0)
; #define PG8_LDA(dst, b, h) do { _Pragma("unroll") for (int m = 0; m < 4; ++m) _Pragma("unroll") for (int k = 0; k < 2; ++k) dst[m][k] = *(const PG8_LAS bf16x8*)(lds + PG8_SA(b, h) + aoff + m * 2048 + k * 1024); } while (0)
; #define PG8_LDB(dst, b, h) do { _Pragma("unroll") for (int n = 0; n < 2; ++n) _Pragma("unroll") for (int k = 0; k < 2; ++k) dst[n][k] = *(const PG8_LAS bf16x8*)(lds + PG8_SB(b, h) + boff + n * 2048 + k * 1024); } while (0)
; #define PG8_MMA(ai, bj, At, Bt) do { __builtin_amdgcn_s_setprio(1); _Pragma("unroll") for (int m = 0; m < 4; ++m) _Pragma("unroll") for (int n = 0; n < 2; ++n) _Pragma("unroll") for (int k = 0; k < 2; ++k) \
;         acc[ai][bj][m][n] = __builtin_amdgcn_mfma_f32_16x16x32_bf16(Bt[n][k], At[m][k], acc[ai][bj][m][n], 0, 0, 0); __builtin_amdgcn_s_setprio(0); } while (0)
; #define PG8_WAIT_V(n) asm volatile("s_waitcnt vmcnt(" #n ")" ::: "memory")
; #define PG8_WAIT_L(n) asm volatile("s_waitcnt lgkmcnt(" #n ")" ::: "memory")
; #define PG8_BAR __builtin_amdgcn_s_barrier()
; template <class Epi, class Sched, bool ALIGN_EPI = false, bool SP2 = false>
; __device__ __forceinline__ void gemm_phase(PG8_LAS unsigned char* lds, const Gemm g, const Sched& S, const Epi& E) {
;     ...
;             const char* a1 = cA + (size_t)(t + 1) * kstep;
;             const char* a2 = last ? nA : cA + (size_t)(t + 2) * kstep; const char* b2 = last ? nB : cB + (size_t)(t + 2) * kstep;
;             const char* a3 = a2 + kstep; const char* b3 = b2 + kstep;
;             if (last && has_next) S.a_ready(nxt);
;             if constexpr (SP2) {
;             PG8_LDB(B0, 0, 0); PG8_LDB(B1, 0, 1); PG8_SCHED; PG8_LDA(At, 0, 0); PG8_STAGE(PG8_SA(1, 1), a1 + hstep, voffA);
;             PG8_WAIT_V(8); PG8_WAIT_L(0); PG8_BAR; PG8_MMA(0, 0, At, B0); PG8_MMA(0, 1, At, B1); PG8_BAR; PG8_SCHED;
;             PG8_LDA(At, 0, 1); PG8_STAGE(PG8_SB(0, 0), b2, voffB); PG8_STAGE(PG8_SB(0, 1), b2 + hstepB, voffB); PG8_STAGE(PG8_SA(0, 0), a2, voffA);
;             PG8_WAIT_V(8); PG8_WAIT_L(0); PG8_BAR; PG8_MMA(1, 0, At, B0); PG8_MMA(1, 1, At, B1); PG8_BAR; PG8_SCHED;
.LBB0_1071:
	s_add_u32 s10, s38, 0xffe00080
	s_addc_u32 s11, s39, -1
	s_add_i32 s12, 0, 0x10000
	s_cmpk_eq_i32 s9, 0x7c
	s_cselect_b32 vcc_hi, s97, s11
	s_cselect_b32 vcc_lo, s4, s10
	s_cselect_b32 s47, s5, s8
	s_cselect_b32 s46, s6, s7
	s_add_i32 s13, 0, 0x14000
	v_add_u32_e32 v152, s12, v164
	v_add_u32_e32 v167, s13, v164
	ds_read_b128 v[130:133], v152
	ds_read_b128 v[134:137], v152 offset:1024
	ds_read_b128 v[138:141], v152 offset:2048
	ds_read_b128 v[152:155], v152 offset:3072
	ds_read_b128 v[156:159], v167
	ds_read_b128 v[160:163], v167 offset:1024
	ds_read_b128 v[168:171], v167 offset:2048
	ds_read_b128 v[172:175], v167 offset:3072
	v_lshl_add_u64 v[184:185], s[38:39], 0, v[148:149]
	s_add_i32 m0, s74, 0xc000
	ds_read_b128 v[176:179], v166
	ds_read_b128 v[180:183], v166 offset:1024
	ds_read_b128 v[206:209], v166 offset:2048
	ds_read_b128 v[210:213], v166 offset:3072
	ds_read_b128 v[214:217], v166 offset:4096
	ds_read_b128 v[218:221], v166 offset:5120
	ds_read_b128 v[236:239], v166 offset:6144
	ds_read_b128 v[240:243], v166 offset:7168
	global_load_lds_dwordx4 v[184:185], off
	s_add_i32 m0, s74, 0xe000
	v_lshl_add_u64 v[184:185], s[38:39], 0, v[150:151]
	global_load_lds_dwordx4 v[184:185], off
	s_waitcnt vmcnt(8)
	s_waitcnt lgkmcnt(0)
	s_barrier
	v_mfma_f32_16x16x32_bf16 v[126:129], v[130:133], v[176:179], v[126:129]
	v_mfma_f32_16x16x32_bf16 v[122:125], v[138:141], v[176:179], v[122:125]
	v_mfma_f32_16x16x32_bf16 v[110:113], v[130:133], v[206:209], v[110:113]
	v_mfma_f32_16x16x32_bf16 v[106:109], v[138:141], v[206:209], v[106:109]
	v_mfma_f32_16x16x32_bf16 v[94:97], v[130:133], v[214:217], v[94:97]
	v_mfma_f32_16x16x32_bf16 v[90:93], v[138:141], v[214:217], v[90:93]
	v_mfma_f32_16x16x32_bf16 v[78:81], v[130:133], v[236:239], v[78:81]
	v_mfma_f32_16x16x32_bf16 v[74:77], v[138:141], v[236:239], v[74:77]
	v_mfma_f32_16x16x32_bf16 v[126:129], v[134:137], v[180:183], v[126:129]
	v_mfma_f32_16x16x32_bf16 v[122:125], v[152:155], v[180:183], v[122:125]
	v_mfma_f32_16x16x32_bf16 v[110:113], v[134:137], v[210:213], v[110:113]
	v_mfma_f32_16x16x32_bf16 v[106:109], v[152:155], v[210:213], v[106:109]
	v_mfma_f32_16x16x32_bf16 v[94:97], v[134:137], v[218:221], v[94:97]
	v_mfma_f32_16x16x32_bf16 v[90:93], v[152:155], v[218:221], v[90:93]
	v_mfma_f32_16x16x32_bf16 v[78:81], v[134:137], v[240:243], v[78:81]
	v_mfma_f32_16x16x32_bf16 v[74:77], v[152:155], v[240:243], v[74:77]
	v_mfma_f32_16x16x32_bf16 v[118:121], v[156:159], v[176:179], v[118:121]
	v_mfma_f32_16x16x32_bf16 v[114:117], v[168:171], v[176:179], v[114:117]
	v_mfma_f32_16x16x32_bf16 v[102:105], v[156:159], v[206:209], v[102:105]
	v_mfma_f32_16x16x32_bf16 v[98:101], v[168:171], v[206:209], v[98:101]
	v_mfma_f32_16x16x32_bf16 v[86:89], v[156:159], v[214:217], v[86:89]
	v_mfma_f32_16x16x32_bf16 v[82:85], v[168:171], v[214:217], v[82:85]
	v_mfma_f32_16x16x32_bf16 v[70:73], v[156:159], v[236:239], v[70:73]
	v_mfma_f32_16x16x32_bf16 v[66:69], v[168:171], v[236:239], v[66:69]
	v_mfma_f32_16x16x32_bf16 v[118:121], v[160:163], v[180:183], v[118:121]
	v_mfma_f32_16x16x32_bf16 v[114:117], v[172:175], v[180:183], v[114:117]
	v_mfma_f32_16x16x32_bf16 v[102:105], v[160:163], v[210:213], v[102:105]
	v_mfma_f32_16x16x32_bf16 v[98:101], v[172:175], v[210:213], v[98:101]
	v_mfma_f32_16x16x32_bf16 v[86:89], v[160:163], v[218:221], v[86:89]
	v_mfma_f32_16x16x32_bf16 v[82:85], v[172:175], v[218:221], v[82:85]
	v_mfma_f32_16x16x32_bf16 v[70:73], v[160:163], v[240:243], v[70:73]
	v_mfma_f32_16x16x32_bf16 v[66:69], v[172:175], v[240:243], v[66:69]
	s_barrier
	s_add_i32 s10, s12, s67
	v_lshl_add_u64 v[184:185], s[46:47], 0, v[146:147]
	s_mov_b32 m0, s10
	ds_read_b128 v[176:179], v166 offset:16384
	ds_read_b128 v[180:183], v166 offset:17408
	ds_read_b128 v[206:209], v166 offset:18432
	ds_read_b128 v[210:213], v166 offset:19456
	ds_read_b128 v[214:217], v166 offset:20480
	ds_read_b128 v[218:221], v166 offset:21504
	ds_read_b128 v[236:239], v166 offset:22528
	ds_read_b128 v[240:243], v166 offset:23552
	global_load_lds_dwordx4 v[184:185], off
	s_add_i32 m0, s10, 0x2000
	s_add_u32 s10, s46, 0x80000
	v_lshl_add_u64 v[194:195], s[46:47], 0, v[142:143]
	s_addc_u32 s11, s47, 0
	s_add_i32 s12, s13, s67
	global_load_lds_dwordx4 v[194:195], off
	v_lshl_add_u64 v[196:197], s[10:11], 0, v[146:147]
	s_mov_b32 m0, s12
	v_lshl_add_u64 v[198:199], vcc, 0, v[144:145]
	global_load_lds_dwordx4 v[196:197], off
	s_add_i32 m0, s12, 0x2000
	v_lshl_add_u64 v[196:197], s[10:11], 0, v[142:143]
	global_load_lds_dwordx4 v[196:197], off
	s_mov_b32 m0, s74
	v_lshl_add_u64 v[196:197], vcc, 0, v[190:191]
	global_load_lds_dwordx4 v[196:197], off
	s_mov_b32 m0, s75
	s_nop 0
	global_load_lds_dwordx4 v[198:199], off
	s_waitcnt vmcnt(8)
	s_waitcnt lgkmcnt(0)
	s_barrier
; #define PG8_STAGE(bufoff, gbase, voff) do { _Pragma("unroll") for (int _i = 0; _i < 2; ++_i) \
;         __builtin_amdgcn_global_load_lds((const unsigned*)((const char*)(gbase) + (voff)[_i]), (PG8_LAS unsigned*)(lds + (bufoff) + ldsw + _i * 8192), 16, 0, 0); } while (0)
; #define PG8_LDA(dst, b, h) do { _Pragma("unroll") for (int m = 0; m < 4; ++m) _Pragma("unroll") for (int k = 0; k < 2; ++k) dst[m][k] = *(const PG8_LAS bf16x8*)(lds + PG8_SA(b, h) + aoff + m * 2048 + k * 1024); } while (0)
; #define PG8_LDB(dst, b, h) do { _Pragma("unroll") for (int n = 0; n < 2; ++n) _Pragma("unroll") for (int k = 0; k < 2; ++k) dst[n][k] = *(const PG8_LAS bf16x8*)(lds + PG8_SB(b, h) + boff + n * 2048 + k * 1024); } while (0)
; #define PG8_MMA(ai, bj, At, Bt) do { __builtin_amdgcn_s_setprio(1); _Pragma("unroll") for (int m = 0; m < 4; ++m) _Pragma("unroll") for (int n = 0; n < 2; ++n) _Pragma("unroll") for (int k = 0; k < 2; ++k) \
;         acc[ai][bj][m][n] = __builtin_amdgcn_mfma_f32_16x16x32_bf16(Bt[n][k], At[m][k], acc[ai][bj][m][n], 0, 0, 0); __builtin_amdgcn_s_setprio(0); } while (0)
; #define PG8_WAIT_V(n) asm volatile("s_waitcnt vmcnt(" #n ")" ::: "memory")
; #define PG8_WAIT_L(n) asm volatile("s_waitcnt lgkmcnt(" #n ")" ::: "memory")
; #define PG8_BAR __builtin_amdgcn_s_barrier()
; #define PG8_SCHED __builtin_amdgcn_sched_barrier(0)
; template <class Epi, class Sched, bool ALIGN_EPI = false, bool SP2 = false>
; __device__ __forceinline__ void gemm_phase(PG8_LAS unsigned char* lds, const Gemm g, const Sched& S, const Epi& E) {
;     ...
;             PG8_WAIT_V(8); PG8_WAIT_L(0); PG8_BAR; PG8_MMA(1, 0, At, B0); PG8_MMA(1, 1, At, B1); PG8_BAR; PG8_SCHED;
;             PG8_LDB(B0, 1, 0); PG8_LDB(B1, 1, 1); PG8_SCHED; PG8_LDA(At, 1, 0); PG8_STAGE(PG8_SA(0, 1), a2 + hstep, voffA);
;             PG8_WAIT_V(8); PG8_WAIT_L(0); PG8_BAR; PG8_MMA(0, 0, At, B0); PG8_MMA(0, 1, At, B1); PG8_BAR; PG8_SCHED;
	v_mfma_f32_16x16x32_bf16 v[62:65], v[130:133], v[176:179], v[62:65]
	v_mfma_f32_16x16x32_bf16 v[58:61], v[138:141], v[176:179], v[58:61]
	v_mfma_f32_16x16x32_bf16 v[46:49], v[130:133], v[206:209], v[46:49]
	v_mfma_f32_16x16x32_bf16 v[42:45], v[138:141], v[206:209], v[42:45]
	v_mfma_f32_16x16x32_bf16 v[30:33], v[130:133], v[214:217], v[30:33]
	v_mfma_f32_16x16x32_bf16 v[26:29], v[138:141], v[214:217], v[26:29]
	v_mfma_f32_16x16x32_bf16 v[14:17], v[130:133], v[236:239], v[14:17]
	v_mfma_f32_16x16x32_bf16 v[10:13], v[138:141], v[236:239], v[10:13]
	v_mfma_f32_16x16x32_bf16 v[62:65], v[134:137], v[180:183], v[62:65]
	v_mfma_f32_16x16x32_bf16 v[58:61], v[152:155], v[180:183], v[58:61]
	v_mfma_f32_16x16x32_bf16 v[46:49], v[134:137], v[210:213], v[46:49]
	v_mfma_f32_16x16x32_bf16 v[42:45], v[152:155], v[210:213], v[42:45]
	v_mfma_f32_16x16x32_bf16 v[30:33], v[134:137], v[218:221], v[30:33]
	v_mfma_f32_16x16x32_bf16 v[26:29], v[152:155], v[218:221], v[26:29]
	v_mfma_f32_16x16x32_bf16 v[14:17], v[134:137], v[240:243], v[14:17]
	v_mfma_f32_16x16x32_bf16 v[10:13], v[152:155], v[240:243], v[10:13]
	v_mfma_f32_16x16x32_bf16 v[54:57], v[156:159], v[176:179], v[54:57]
	v_mfma_f32_16x16x32_bf16 v[50:53], v[168:171], v[176:179], v[50:53]
	v_mfma_f32_16x16x32_bf16 v[38:41], v[156:159], v[206:209], v[38:41]
	v_mfma_f32_16x16x32_bf16 v[34:37], v[168:171], v[206:209], v[34:37]
	v_mfma_f32_16x16x32_bf16 v[22:25], v[156:159], v[214:217], v[22:25]
	v_mfma_f32_16x16x32_bf16 v[18:21], v[168:171], v[214:217], v[18:21]
	v_mfma_f32_16x16x32_bf16 v[6:9], v[156:159], v[236:239], v[6:9]
	v_mfma_f32_16x16x32_bf16 v[2:5], v[168:171], v[236:239], v[2:5]
	v_mfma_f32_16x16x32_bf16 v[54:57], v[160:163], v[180:183], v[54:57]
	v_mfma_f32_16x16x32_bf16 v[50:53], v[172:175], v[180:183], v[50:53]
	v_mfma_f32_16x16x32_bf16 v[38:41], v[160:163], v[210:213], v[38:41]
	v_mfma_f32_16x16x32_bf16 v[34:37], v[172:175], v[210:213], v[34:37]
	v_mfma_f32_16x16x32_bf16 v[22:25], v[160:163], v[218:221], v[22:25]
	v_mfma_f32_16x16x32_bf16 v[18:21], v[172:175], v[218:221], v[18:21]
	v_mfma_f32_16x16x32_bf16 v[6:9], v[160:163], v[240:243], v[6:9]
	v_mfma_f32_16x16x32_bf16 v[2:5], v[172:175], v[240:243], v[2:5]
	s_barrier
	s_add_i32 s12, 0, 0x18000
	s_add_i32 s13, 0, 0x1c000
	v_add_u32_e32 v152, s12, v164
	v_add_u32_e32 v167, s13, v164
	ds_read_b128 v[130:133], v152
	ds_read_b128 v[134:137], v152 offset:1024
	ds_read_b128 v[138:141], v152 offset:2048
	ds_read_b128 v[152:155], v152 offset:3072
	ds_read_b128 v[156:159], v167
	ds_read_b128 v[160:163], v167 offset:1024
	ds_read_b128 v[168:171], v167 offset:2048
	ds_read_b128 v[172:175], v167 offset:3072
	s_add_u32 s10, vcc_lo, 0x200000
	s_addc_u32 s11, vcc_hi, 0
	s_mov_b32 m0, s86
	v_lshl_add_u64 v[222:223], s[10:11], 0, v[190:191]
	ds_read_b128 v[176:179], v166 offset:32768
	ds_read_b128 v[180:183], v166 offset:33792
	ds_read_b128 v[206:209], v166 offset:34816
	ds_read_b128 v[210:213], v166 offset:35840
	ds_read_b128 v[214:217], v166 offset:36864
	ds_read_b128 v[218:221], v166 offset:37888
	ds_read_b128 v[236:239], v166 offset:38912
	ds_read_b128 v[240:243], v166 offset:39936
	global_load_lds_dwordx4 v[222:223], off
	s_mov_b32 m0, s87
	v_lshl_add_u64 v[222:223], s[10:11], 0, v[144:145]
	global_load_lds_dwordx4 v[222:223], off
	s_waitcnt vmcnt(8)
	s_waitcnt lgkmcnt(0)
	s_barrier
	v_mfma_f32_16x16x32_bf16 v[126:129], v[130:133], v[176:179], v[126:129]
	v_mfma_f32_16x16x32_bf16 v[122:125], v[138:141], v[176:179], v[122:125]
	v_mfma_f32_16x16x32_bf16 v[110:113], v[130:133], v[206:209], v[110:113]
	v_mfma_f32_16x16x32_bf16 v[106:109], v[138:141], v[206:209], v[106:109]
	v_mfma_f32_16x16x32_bf16 v[94:97], v[130:133], v[214:217], v[94:97]
	v_mfma_f32_16x16x32_bf16 v[90:93], v[138:141], v[214:217], v[90:93]
	v_mfma_f32_16x16x32_bf16 v[78:81], v[130:133], v[236:239], v[78:81]
	v_mfma_f32_16x16x32_bf16 v[74:77], v[138:141], v[236:239], v[74:77]
	v_mfma_f32_16x16x32_bf16 v[126:129], v[134:137], v[180:183], v[126:129]
	v_mfma_f32_16x16x32_bf16 v[122:125], v[152:155], v[180:183], v[122:125]
	v_mfma_f32_16x16x32_bf16 v[110:113], v[134:137], v[210:213], v[110:113]
	v_mfma_f32_16x16x32_bf16 v[106:109], v[152:155], v[210:213], v[106:109]
	v_mfma_f32_16x16x32_bf16 v[94:97], v[134:137], v[218:221], v[94:97]
	v_mfma_f32_16x16x32_bf16 v[90:93], v[152:155], v[218:221], v[90:93]
	v_mfma_f32_16x16x32_bf16 v[78:81], v[134:137], v[240:243], v[78:81]
	v_mfma_f32_16x16x32_bf16 v[74:77], v[152:155], v[240:243], v[74:77]
	v_mfma_f32_16x16x32_bf16 v[118:121], v[156:159], v[176:179], v[118:121]
	v_mfma_f32_16x16x32_bf16 v[114:117], v[168:171], v[176:179], v[114:117]
	v_mfma_f32_16x16x32_bf16 v[102:105], v[156:159], v[206:209], v[102:105]
	v_mfma_f32_16x16x32_bf16 v[98:101], v[168:171], v[206:209], v[98:101]
	v_mfma_f32_16x16x32_bf16 v[86:89], v[156:159], v[214:217], v[86:89]
	v_mfma_f32_16x16x32_bf16 v[82:85], v[168:171], v[214:217], v[82:85]
	v_mfma_f32_16x16x32_bf16 v[70:73], v[156:159], v[236:239], v[70:73]
	v_mfma_f32_16x16x32_bf16 v[66:69], v[168:171], v[236:239], v[66:69]
	v_mfma_f32_16x16x32_bf16 v[118:121], v[160:163], v[180:183], v[118:121]
	v_mfma_f32_16x16x32_bf16 v[114:117], v[172:175], v[180:183], v[114:117]
	v_mfma_f32_16x16x32_bf16 v[102:105], v[160:163], v[210:213], v[102:105]
	v_mfma_f32_16x16x32_bf16 v[98:101], v[172:175], v[210:213], v[98:101]
	v_mfma_f32_16x16x32_bf16 v[86:89], v[160:163], v[218:221], v[86:89]
	v_mfma_f32_16x16x32_bf16 v[82:85], v[172:175], v[218:221], v[82:85]
	v_mfma_f32_16x16x32_bf16 v[70:73], v[160:163], v[240:243], v[70:73]
	v_mfma_f32_16x16x32_bf16 v[66:69], v[172:175], v[240:243], v[66:69]
	s_barrier
; #define PG8_STAGE(bufoff, gbase, voff) do { _Pragma("unroll") for (int _i = 0; _i < 2; ++_i) \
;         __builtin_amdgcn_global_load_lds((const unsigned*)((const char*)(gbase) + (voff)[_i]), (PG8_LAS unsigned*)(lds + (bufoff) + ldsw + _i * 8192), 16, 0, 0); } while (0)
; #define PG8_LDA(dst, b, h) do { _Pragma("unroll") for (int m = 0; m < 4; ++m) _Pragma("unroll") for (int k = 0; k < 2; ++k) dst[m][k] = *(const PG8_LAS bf16x8*)(lds + PG8_SA(b, h) + aoff + m * 2048 + k * 1024); } while (0)
; #define PG8_MMA(ai, bj, At, Bt) do { __builtin_amdgcn_s_setprio(1); _Pragma("unroll") for (int m = 0; m < 4; ++m) _Pragma("unroll") for (int n = 0; n < 2; ++n) _Pragma("unroll") for (int k = 0; k < 2; ++k) \
;         acc[ai][bj][m][n] = __builtin_amdgcn_mfma_f32_16x16x32_bf16(Bt[n][k], At[m][k], acc[ai][bj][m][n], 0, 0, 0); __builtin_amdgcn_s_setprio(0); } while (0)
; #define PG8_WAIT_V(n) asm volatile("s_waitcnt vmcnt(" #n ")" ::: "memory")
; #define PG8_WAIT_L(n) asm volatile("s_waitcnt lgkmcnt(" #n ")" ::: "memory")
; #define PG8_BAR __builtin_amdgcn_s_barrier()
; #define PG8_SCHED __builtin_amdgcn_sched_barrier(0)
; template <class Epi, class Sched, bool ALIGN_EPI = false, bool SP2 = false>
; __device__ __forceinline__ void gemm_phase(PG8_LAS unsigned char* lds, const Gemm g, const Sched& S, const Epi& E) {
;     ...
;             PG8_LDA(At, 1, 1); PG8_STAGE(PG8_SB(1, 0), b3, voffB); PG8_STAGE(PG8_SB(1, 1), b3 + hstepB, voffB); PG8_STAGE(PG8_SA(1, 0), a3, voffA);
;             PG8_WAIT_V(8); PG8_WAIT_L(0); PG8_BAR; PG8_MMA(1, 0, At, B0); PG8_MMA(1, 1, At, B1); PG8_BAR; PG8_SCHED;
	s_add_i32 s10, s12, s67
	v_lshl_add_u64 v[184:185], v[184:185], 0, s[60:61]
	s_mov_b32 m0, s10
	ds_read_b128 v[176:179], v166 offset:49152
	ds_read_b128 v[180:183], v166 offset:50176
	ds_read_b128 v[206:209], v166 offset:51200
	ds_read_b128 v[210:213], v166 offset:52224
	ds_read_b128 v[214:217], v166 offset:53248
	ds_read_b128 v[218:221], v166 offset:54272
	ds_read_b128 v[236:239], v166 offset:55296
	ds_read_b128 v[240:243], v166 offset:56320
	global_load_lds_dwordx4 v[184:185], off
	s_add_i32 m0, s10, 0x2000
	s_add_u32 s10, s46, 0x80080
	v_lshl_add_u64 v[184:185], v[194:195], 0, s[60:61]
	s_addc_u32 s11, s47, 0
	s_add_i32 s12, s13, s67
	global_load_lds_dwordx4 v[184:185], off
	s_mov_b32 m0, s12
	v_lshl_add_u64 v[184:185], s[10:11], 0, v[146:147]
	global_load_lds_dwordx4 v[184:185], off
	s_add_i32 m0, s12, 0x2000
	v_lshl_add_u64 v[184:185], s[10:11], 0, v[142:143]
	global_load_lds_dwordx4 v[184:185], off
	s_mov_b32 m0, s82
	v_lshl_add_u64 v[184:185], v[196:197], 0, s[60:61]
	global_load_lds_dwordx4 v[184:185], off
	s_mov_b32 m0, s42
	v_lshl_add_u64 v[184:185], v[198:199], 0, s[60:61]
	global_load_lds_dwordx4 v[184:185], off
	s_waitcnt vmcnt(8)
	s_waitcnt lgkmcnt(0)
	s_barrier
	v_mfma_f32_16x16x32_bf16 v[62:65], v[130:133], v[176:179], v[62:65]
	v_mfma_f32_16x16x32_bf16 v[58:61], v[138:141], v[176:179], v[58:61]
	v_mfma_f32_16x16x32_bf16 v[46:49], v[130:133], v[206:209], v[46:49]
	v_mfma_f32_16x16x32_bf16 v[42:45], v[138:141], v[206:209], v[42:45]
	v_mfma_f32_16x16x32_bf16 v[30:33], v[130:133], v[214:217], v[30:33]
	v_mfma_f32_16x16x32_bf16 v[26:29], v[138:141], v[214:217], v[26:29]
	v_mfma_f32_16x16x32_bf16 v[14:17], v[130:133], v[236:239], v[14:17]
	v_mfma_f32_16x16x32_bf16 v[10:13], v[138:141], v[236:239], v[10:13]
	v_mfma_f32_16x16x32_bf16 v[62:65], v[134:137], v[180:183], v[62:65]
	v_mfma_f32_16x16x32_bf16 v[58:61], v[152:155], v[180:183], v[58:61]
	v_mfma_f32_16x16x32_bf16 v[46:49], v[134:137], v[210:213], v[46:49]
	v_mfma_f32_16x16x32_bf16 v[42:45], v[152:155], v[210:213], v[42:45]
	v_mfma_f32_16x16x32_bf16 v[30:33], v[134:137], v[218:221], v[30:33]
	v_mfma_f32_16x16x32_bf16 v[26:29], v[152:155], v[218:221], v[26:29]
	v_mfma_f32_16x16x32_bf16 v[14:17], v[134:137], v[240:243], v[14:17]
	v_mfma_f32_16x16x32_bf16 v[10:13], v[152:155], v[240:243], v[10:13]
	v_mfma_f32_16x16x32_bf16 v[54:57], v[156:159], v[176:179], v[54:57]
	v_mfma_f32_16x16x32_bf16 v[50:53], v[168:171], v[176:179], v[50:53]
	v_mfma_f32_16x16x32_bf16 v[38:41], v[156:159], v[206:209], v[38:41]
	v_mfma_f32_16x16x32_bf16 v[34:37], v[168:171], v[206:209], v[34:37]
	v_mfma_f32_16x16x32_bf16 v[22:25], v[156:159], v[214:217], v[22:25]
	v_mfma_f32_16x16x32_bf16 v[18:21], v[168:171], v[214:217], v[18:21]
	v_mfma_f32_16x16x32_bf16 v[6:9], v[156:159], v[236:239], v[6:9]
	v_mfma_f32_16x16x32_bf16 v[2:5], v[168:171], v[236:239], v[2:5]
	v_mfma_f32_16x16x32_bf16 v[54:57], v[160:163], v[180:183], v[54:57]
	v_mfma_f32_16x16x32_bf16 v[50:53], v[172:175], v[180:183], v[50:53]
	v_mfma_f32_16x16x32_bf16 v[38:41], v[160:163], v[210:213], v[38:41]
	v_mfma_f32_16x16x32_bf16 v[34:37], v[172:175], v[210:213], v[34:37]
	v_mfma_f32_16x16x32_bf16 v[22:25], v[160:163], v[218:221], v[22:25]
	v_mfma_f32_16x16x32_bf16 v[18:21], v[172:175], v[218:221], v[18:21]
	v_mfma_f32_16x16x32_bf16 v[6:9], v[160:163], v[240:243], v[6:9]
	v_mfma_f32_16x16x32_bf16 v[2:5], v[172:175], v[240:243], v[2:5]
	s_barrier
	s_add_i32 s9, s9, 2
	s_add_u32 s38, s38, 0x100
	s_addc_u32 s39, s39, 0
	s_add_u32 s7, s7, 0x100
	s_addc_u32 s8, s8, 0
	s_cmpk_gt_u32 s9, 0x7d
	s_cbranch_scc0 .LBB0_1071
	s_and_b64 vcc, exec, s[72:73]
	s_cbranch_vccz .LBB0_1074
	s_barrier

; #define PG8_STAGE(bufoff, gbase, voff) do { _Pragma("unroll") for (int _i = 0; _i < 2; ++_i) \
;         __builtin_amdgcn_global_load_lds((const unsigned*)((const char*)(gbase) + (voff)[_i]), (PG8_LAS unsigned*)(lds + (bufoff) + ldsw + _i * 8192), 16, 0, 0); } while (0)
; #define PG8_LDA(dst, b, h) do { _Pragma("unroll") for (int m = 0; m < 4; ++m) _Pragma("unroll") for (int k = 0; k < 2; ++k) dst[m][k] = *(const PG8_LAS bf16x8*)(lds + PG8_SA(b, h) + aoff + m * 2048 + k * 1024); } while (0)
; #define PG8_LDB(dst, b, h) do { _Pragma("unroll") for (int n = 0; n < 2; ++n) _Pragma("unroll") for (int k = 0; k < 2; ++k) dst[n][k] = *(const PG8_LAS bf16x8*)(lds + PG8_SB(b, h) + boff + n * 2048 + k * 1024); } while (0)
; #define PG8_MMA(ai, bj, At, Bt) do { __builtin_amdgcn_s_setprio(1); _Pragma("unroll") for (int m = 0; m < 4; ++m) _Pragma("unroll") for (int n = 0; n < 2; ++n) _Pragma("unroll") for (int k = 0; k < 2; ++k) \
;         acc[ai][bj][m][n] = __builtin_amdgcn_mfma_f32_16x16x32_bf16(Bt[n][k], At[m][k], acc[ai][bj][m][n], 0, 0, 0); __builtin_amdgcn_s_setprio(0); } while (0)
; #define PG8_WAIT_V(n) asm volatile("s_waitcnt vmcnt(" #n ")" ::: "memory")
; #define PG8_WAIT_L(n) asm volatile("s_waitcnt lgkmcnt(" #n ")" ::: "memory")
; #define PG8_BAR __builtin_amdgcn_s_barrier()
; template <class Epi, class Sched, bool ALIGN_EPI = false, bool SP2 = false>
; __device__ __forceinline__ void gemm_phase(PG8_LAS unsigned char* lds, const Gemm g, const Sched& S, const Epi& E) {
;     ...
;             const char* a1 = cA + (size_t)(t + 1) * kstep;
;             const char* a2 = last ? nA : cA + (size_t)(t + 2) * kstep; const char* b2 = last ? nB : cB + (size_t)(t + 2) * kstep;
;             const char* a3 = a2 + kstep; const char* b3 = b2 + kstep;
;             if (last && has_next) S.a_ready(nxt);
;             if constexpr (SP2) {
;             PG8_LDB(B0, 0, 0); PG8_LDB(B1, 0, 1); PG8_SCHED; PG8_LDA(At, 0, 0); PG8_STAGE(PG8_SA(1, 1), a1 + hstep, voffA);
;             PG8_WAIT_V(8); PG8_WAIT_L(0); PG8_BAR; PG8_MMA(0, 0, At, B0); PG8_MMA(0, 1, At, B1); PG8_BAR; PG8_SCHED;
;             PG8_LDA(At, 0, 1); PG8_STAGE(PG8_SB(0, 0), b2, voffB); PG8_STAGE(PG8_SB(0, 1), b2 + hstepB, voffB); PG8_STAGE(PG8_SA(0, 0), a2, voffA);
;             PG8_WAIT_V(8); PG8_WAIT_L(0); PG8_BAR; PG8_MMA(1, 0, At, B0); PG8_MMA(1, 1, At, B1); PG8_BAR; PG8_SCHED;
.LBB0_1233:
	s_add_u32 s9, s68, s80
	s_addc_u32 s10, s69, s81
	s_add_u32 s9, s9, 0x100
	s_addc_u32 s10, s10, 0
	s_add_u32 s11, s36, s80
	s_addc_u32 s12, s37, s81
	s_add_i32 s13, 0, 0x10000
	s_cmpk_eq_i32 s80, 0xf00
	s_cselect_b32 s93, s4, s10
	s_cselect_b32 s92, s5, s9
	v_add_u32_e32 v144, s13, v145
	s_cselect_b32 s85, s6, s12
	s_cselect_b32 s84, s7, s11
	s_add_i32 s9, 0, 0x14000
	ds_read_b128 v[152:155], v144
	ds_read_b128 v[156:159], v144 offset:1024
	ds_read_b128 v[160:163], v144 offset:2048
	ds_read_b128 v[164:167], v144 offset:3072
	v_add_u32_e32 v144, s9, v145
	ds_read_b128 v[168:171], v144
	ds_read_b128 v[172:175], v144 offset:1024
	ds_read_b128 v[176:179], v144 offset:2048
	ds_read_b128 v[180:183], v144 offset:3072
	v_lshl_add_u64 v[184:185], v[140:141], 0, s[80:81]
	s_add_i32 m0, s51, 0xc000
	ds_read_b128 v[206:209], v151
	ds_read_b128 v[210:213], v151 offset:1024
	ds_read_b128 v[214:217], v151 offset:2048
	ds_read_b128 v[218:221], v151 offset:3072
	ds_read_b128 v[236:239], v151 offset:4096
	ds_read_b128 v[240:243], v151 offset:5120
	ds_read_b128 v[244:247], v151 offset:6144
	ds_read_b128 v[194:197], v151 offset:7168
	global_load_lds_dwordx4 v[184:185], off
	s_add_i32 m0, s51, 0xe000
	v_lshl_add_u64 v[184:185], v[142:143], 0, s[80:81]
	global_load_lds_dwordx4 v[184:185], off
	s_waitcnt vmcnt(8)
	s_waitcnt lgkmcnt(0)
	s_barrier
	v_mfma_f32_16x16x32_bf16 v[126:129], v[152:155], v[206:209], v[126:129]
	v_mfma_f32_16x16x32_bf16 v[122:125], v[160:163], v[206:209], v[122:125]
	v_mfma_f32_16x16x32_bf16 v[118:121], v[152:155], v[214:217], v[118:121]
	v_mfma_f32_16x16x32_bf16 v[114:117], v[160:163], v[214:217], v[114:117]
	v_mfma_f32_16x16x32_bf16 v[110:113], v[152:155], v[236:239], v[110:113]
	v_mfma_f32_16x16x32_bf16 v[106:109], v[160:163], v[236:239], v[106:109]
	v_mfma_f32_16x16x32_bf16 v[102:105], v[152:155], v[244:247], v[102:105]
	v_mfma_f32_16x16x32_bf16 v[98:101], v[160:163], v[244:247], v[98:101]
	v_mfma_f32_16x16x32_bf16 v[126:129], v[156:159], v[210:213], v[126:129]
	v_mfma_f32_16x16x32_bf16 v[122:125], v[164:167], v[210:213], v[122:125]
	v_mfma_f32_16x16x32_bf16 v[118:121], v[156:159], v[218:221], v[118:121]
	v_mfma_f32_16x16x32_bf16 v[114:117], v[164:167], v[218:221], v[114:117]
	v_mfma_f32_16x16x32_bf16 v[110:113], v[156:159], v[240:243], v[110:113]
	v_mfma_f32_16x16x32_bf16 v[106:109], v[164:167], v[240:243], v[106:109]
	v_mfma_f32_16x16x32_bf16 v[102:105], v[156:159], v[194:197], v[102:105]
	v_mfma_f32_16x16x32_bf16 v[98:101], v[164:167], v[194:197], v[98:101]
	v_mfma_f32_16x16x32_bf16 v[94:97], v[168:171], v[206:209], v[94:97]
	v_mfma_f32_16x16x32_bf16 v[90:93], v[176:179], v[206:209], v[90:93]
	v_mfma_f32_16x16x32_bf16 v[86:89], v[168:171], v[214:217], v[86:89]
	v_mfma_f32_16x16x32_bf16 v[82:85], v[176:179], v[214:217], v[82:85]
	v_mfma_f32_16x16x32_bf16 v[78:81], v[168:171], v[236:239], v[78:81]
	v_mfma_f32_16x16x32_bf16 v[74:77], v[176:179], v[236:239], v[74:77]
	v_mfma_f32_16x16x32_bf16 v[70:73], v[168:171], v[244:247], v[70:73]
	v_mfma_f32_16x16x32_bf16 v[66:69], v[176:179], v[244:247], v[66:69]
	v_mfma_f32_16x16x32_bf16 v[94:97], v[172:175], v[210:213], v[94:97]
	v_mfma_f32_16x16x32_bf16 v[90:93], v[180:183], v[210:213], v[90:93]
	v_mfma_f32_16x16x32_bf16 v[86:89], v[172:175], v[218:221], v[86:89]
	v_mfma_f32_16x16x32_bf16 v[82:85], v[180:183], v[218:221], v[82:85]
	v_mfma_f32_16x16x32_bf16 v[78:81], v[172:175], v[240:243], v[78:81]
	v_mfma_f32_16x16x32_bf16 v[74:77], v[180:183], v[240:243], v[74:77]
	v_mfma_f32_16x16x32_bf16 v[70:73], v[172:175], v[194:197], v[70:73]
	v_mfma_f32_16x16x32_bf16 v[66:69], v[180:183], v[194:197], v[66:69]
	s_barrier
	s_add_i32 s10, s13, s42
	v_lshl_add_u64 v[184:185], s[84:85], 0, v[130:131]
	s_mov_b32 m0, s10
	ds_read_b128 v[194:197], v151 offset:16384
	ds_read_b128 v[206:209], v151 offset:17408
	ds_read_b128 v[210:213], v151 offset:18432
	ds_read_b128 v[214:217], v151 offset:19456
	ds_read_b128 v[218:221], v151 offset:20480
	ds_read_b128 v[236:239], v151 offset:21504
	ds_read_b128 v[240:243], v151 offset:22528
	ds_read_b128 v[244:247], v151 offset:23552
	global_load_lds_dwordx4 v[184:185], off
	s_add_i32 m0, s10, 0x2000
	s_add_u32 s10, s84, 0x20000
	v_lshl_add_u64 v[198:199], s[84:85], 0, v[134:135]
	s_addc_u32 s11, s85, 0
	s_add_i32 s9, s9, s42
	global_load_lds_dwordx4 v[198:199], off
	v_lshl_add_u64 v[222:223], s[10:11], 0, v[130:131]
	s_mov_b32 m0, s9
	v_lshl_add_u64 v[234:235], s[92:93], 0, v[132:133]
	global_load_lds_dwordx4 v[222:223], off
	s_add_i32 m0, s9, 0x2000
	v_lshl_add_u64 v[222:223], s[10:11], 0, v[134:135]
	global_load_lds_dwordx4 v[222:223], off
	s_mov_b32 m0, s51
	v_lshl_add_u64 v[222:223], s[92:93], 0, v[190:191]
	global_load_lds_dwordx4 v[222:223], off
	s_mov_b32 m0, s67
	s_nop 0
	global_load_lds_dwordx4 v[234:235], off
	s_waitcnt vmcnt(8)
	s_waitcnt lgkmcnt(0)
	s_barrier
; #define PG8_STAGE(bufoff, gbase, voff) do { _Pragma("unroll") for (int _i = 0; _i < 2; ++_i) \
;         __builtin_amdgcn_global_load_lds((const unsigned*)((const char*)(gbase) + (voff)[_i]), (PG8_LAS unsigned*)(lds + (bufoff) + ldsw + _i * 8192), 16, 0, 0); } while (0)
; #define PG8_LDA(dst, b, h) do { _Pragma("unroll") for (int m = 0; m < 4; ++m) _Pragma("unroll") for (int k = 0; k < 2; ++k) dst[m][k] = *(const PG8_LAS bf16x8*)(lds + PG8_SA(b, h) + aoff + m * 2048 + k * 1024); } while (0)
; #define PG8_LDB(dst, b, h) do { _Pragma("unroll") for (int n = 0; n < 2; ++n) _Pragma("unroll") for (int k = 0; k < 2; ++k) dst[n][k] = *(const PG8_LAS bf16x8*)(lds + PG8_SB(b, h) + boff + n * 2048 + k * 1024); } while (0)
; #define PG8_MMA(ai, bj, At, Bt) do { __builtin_amdgcn_s_setprio(1); _Pragma("unroll") for (int m = 0; m < 4; ++m) _Pragma("unroll") for (int n = 0; n < 2; ++n) _Pragma("unroll") for (int k = 0; k < 2; ++k) \
;         acc[ai][bj][m][n] = __builtin_amdgcn_mfma_f32_16x16x32_bf16(Bt[n][k], At[m][k], acc[ai][bj][m][n], 0, 0, 0); __builtin_amdgcn_s_setprio(0); } while (0)
; #define PG8_WAIT_V(n) asm volatile("s_waitcnt vmcnt(" #n ")" ::: "memory")
; #define PG8_WAIT_L(n) asm volatile("s_waitcnt lgkmcnt(" #n ")" ::: "memory")
; #define PG8_BAR __builtin_amdgcn_s_barrier()
; #define PG8_SCHED __builtin_amdgcn_sched_barrier(0)
; template <class Epi, class Sched, bool ALIGN_EPI = false, bool SP2 = false>
; __device__ __forceinline__ void gemm_phase(PG8_LAS unsigned char* lds, const Gemm g, const Sched& S, const Epi& E) {
;     ...
;             PG8_WAIT_V(8); PG8_WAIT_L(0); PG8_BAR; PG8_MMA(1, 0, At, B0); PG8_MMA(1, 1, At, B1); PG8_BAR; PG8_SCHED;
;             PG8_LDB(B0, 1, 0); PG8_LDB(B1, 1, 1); PG8_SCHED; PG8_LDA(At, 1, 0); PG8_STAGE(PG8_SA(0, 1), a2 + hstep, voffA);
;             PG8_WAIT_V(8); PG8_WAIT_L(0); PG8_BAR; PG8_MMA(0, 0, At, B0); PG8_MMA(0, 1, At, B1); PG8_BAR; PG8_SCHED;
	v_mfma_f32_16x16x32_bf16 v[62:65], v[152:155], v[194:197], v[62:65]
	v_mfma_f32_16x16x32_bf16 v[58:61], v[160:163], v[194:197], v[58:61]
	v_mfma_f32_16x16x32_bf16 v[54:57], v[152:155], v[210:213], v[54:57]
	v_mfma_f32_16x16x32_bf16 v[50:53], v[160:163], v[210:213], v[50:53]
	v_mfma_f32_16x16x32_bf16 v[46:49], v[152:155], v[218:221], v[46:49]
	v_mfma_f32_16x16x32_bf16 v[42:45], v[160:163], v[218:221], v[42:45]
	v_mfma_f32_16x16x32_bf16 v[38:41], v[152:155], v[240:243], v[38:41]
	v_mfma_f32_16x16x32_bf16 v[34:37], v[160:163], v[240:243], v[34:37]
	v_mfma_f32_16x16x32_bf16 v[62:65], v[156:159], v[206:209], v[62:65]
	v_mfma_f32_16x16x32_bf16 v[58:61], v[164:167], v[206:209], v[58:61]
	v_mfma_f32_16x16x32_bf16 v[54:57], v[156:159], v[214:217], v[54:57]
	v_mfma_f32_16x16x32_bf16 v[50:53], v[164:167], v[214:217], v[50:53]
	v_mfma_f32_16x16x32_bf16 v[46:49], v[156:159], v[236:239], v[46:49]
	v_mfma_f32_16x16x32_bf16 v[42:45], v[164:167], v[236:239], v[42:45]
	v_mfma_f32_16x16x32_bf16 v[38:41], v[156:159], v[244:247], v[38:41]
	v_mfma_f32_16x16x32_bf16 v[34:37], v[164:167], v[244:247], v[34:37]
	v_mfma_f32_16x16x32_bf16 v[30:33], v[168:171], v[194:197], v[30:33]
	v_mfma_f32_16x16x32_bf16 v[26:29], v[176:179], v[194:197], v[26:29]
	v_mfma_f32_16x16x32_bf16 v[22:25], v[168:171], v[210:213], v[22:25]
	v_mfma_f32_16x16x32_bf16 v[18:21], v[176:179], v[210:213], v[18:21]
	v_mfma_f32_16x16x32_bf16 v[14:17], v[168:171], v[218:221], v[14:17]
	v_mfma_f32_16x16x32_bf16 v[10:13], v[176:179], v[218:221], v[10:13]
	v_mfma_f32_16x16x32_bf16 v[6:9], v[168:171], v[240:243], v[6:9]
	v_mfma_f32_16x16x32_bf16 v[2:5], v[176:179], v[240:243], v[2:5]
	v_mfma_f32_16x16x32_bf16 v[30:33], v[172:175], v[206:209], v[30:33]
	v_mfma_f32_16x16x32_bf16 v[26:29], v[180:183], v[206:209], v[26:29]
	v_mfma_f32_16x16x32_bf16 v[22:25], v[172:175], v[214:217], v[22:25]
	v_mfma_f32_16x16x32_bf16 v[18:21], v[180:183], v[214:217], v[18:21]
	v_mfma_f32_16x16x32_bf16 v[14:17], v[172:175], v[236:239], v[14:17]
	v_mfma_f32_16x16x32_bf16 v[10:13], v[180:183], v[236:239], v[10:13]
	v_mfma_f32_16x16x32_bf16 v[6:9], v[172:175], v[244:247], v[6:9]
	v_mfma_f32_16x16x32_bf16 v[2:5], v[180:183], v[244:247], v[2:5]
	s_barrier
	s_add_i32 s9, 0, 0x18000
	v_add_u32_e32 v144, s9, v145
	s_add_i32 s12, 0, 0x1c000
	ds_read_b128 v[152:155], v144
	ds_read_b128 v[156:159], v144 offset:1024
	ds_read_b128 v[160:163], v144 offset:2048
	ds_read_b128 v[164:167], v144 offset:3072
	v_add_u32_e32 v144, s12, v145
	ds_read_b128 v[168:171], v144
	ds_read_b128 v[172:175], v144 offset:1024
	ds_read_b128 v[176:179], v144 offset:2048
	ds_read_b128 v[180:183], v144 offset:3072
	s_add_u32 s10, s92, 0x80000
	s_addc_u32 s11, s93, 0
	s_mov_b32 m0, s74
	v_lshl_add_u64 v[186:187], s[10:11], 0, v[190:191]
	ds_read_b128 v[194:197], v151 offset:32768
	ds_read_b128 v[206:209], v151 offset:33792
	ds_read_b128 v[210:213], v151 offset:34816
	ds_read_b128 v[214:217], v151 offset:35840
	ds_read_b128 v[218:221], v151 offset:36864
	ds_read_b128 v[236:239], v151 offset:37888
	ds_read_b128 v[240:243], v151 offset:38912
	ds_read_b128 v[244:247], v151 offset:39936
	global_load_lds_dwordx4 v[186:187], off
	s_mov_b32 m0, s75
	v_lshl_add_u64 v[186:187], s[10:11], 0, v[132:133]
	global_load_lds_dwordx4 v[186:187], off
	s_waitcnt vmcnt(8)
	s_waitcnt lgkmcnt(0)
	s_barrier
	v_mfma_f32_16x16x32_bf16 v[126:129], v[152:155], v[194:197], v[126:129]
	v_mfma_f32_16x16x32_bf16 v[122:125], v[160:163], v[194:197], v[122:125]
	v_mfma_f32_16x16x32_bf16 v[118:121], v[152:155], v[210:213], v[118:121]
	v_mfma_f32_16x16x32_bf16 v[114:117], v[160:163], v[210:213], v[114:117]
	v_mfma_f32_16x16x32_bf16 v[110:113], v[152:155], v[218:221], v[110:113]
	v_mfma_f32_16x16x32_bf16 v[106:109], v[160:163], v[218:221], v[106:109]
	v_mfma_f32_16x16x32_bf16 v[102:105], v[152:155], v[240:243], v[102:105]
	v_mfma_f32_16x16x32_bf16 v[98:101], v[160:163], v[240:243], v[98:101]
	v_mfma_f32_16x16x32_bf16 v[126:129], v[156:159], v[206:209], v[126:129]
	v_mfma_f32_16x16x32_bf16 v[122:125], v[164:167], v[206:209], v[122:125]
	v_mfma_f32_16x16x32_bf16 v[118:121], v[156:159], v[214:217], v[118:121]
	v_mfma_f32_16x16x32_bf16 v[114:117], v[164:167], v[214:217], v[114:117]
	v_mfma_f32_16x16x32_bf16 v[110:113], v[156:159], v[236:239], v[110:113]
	v_mfma_f32_16x16x32_bf16 v[106:109], v[164:167], v[236:239], v[106:109]
	v_mfma_f32_16x16x32_bf16 v[102:105], v[156:159], v[244:247], v[102:105]
	v_mfma_f32_16x16x32_bf16 v[98:101], v[164:167], v[244:247], v[98:101]
	v_mfma_f32_16x16x32_bf16 v[94:97], v[168:171], v[194:197], v[94:97]
	v_mfma_f32_16x16x32_bf16 v[90:93], v[176:179], v[194:197], v[90:93]
	v_mfma_f32_16x16x32_bf16 v[86:89], v[168:171], v[210:213], v[86:89]
	v_mfma_f32_16x16x32_bf16 v[82:85], v[176:179], v[210:213], v[82:85]
	v_mfma_f32_16x16x32_bf16 v[78:81], v[168:171], v[218:221], v[78:81]
	v_mfma_f32_16x16x32_bf16 v[74:77], v[176:179], v[218:221], v[74:77]
	v_mfma_f32_16x16x32_bf16 v[70:73], v[168:171], v[240:243], v[70:73]
	v_mfma_f32_16x16x32_bf16 v[66:69], v[176:179], v[240:243], v[66:69]
	v_mfma_f32_16x16x32_bf16 v[94:97], v[172:175], v[206:209], v[94:97]
	v_mfma_f32_16x16x32_bf16 v[90:93], v[180:183], v[206:209], v[90:93]
	v_mfma_f32_16x16x32_bf16 v[86:89], v[172:175], v[214:217], v[86:89]
	v_mfma_f32_16x16x32_bf16 v[82:85], v[180:183], v[214:217], v[82:85]
	v_mfma_f32_16x16x32_bf16 v[78:81], v[172:175], v[236:239], v[78:81]
	v_mfma_f32_16x16x32_bf16 v[74:77], v[180:183], v[236:239], v[74:77]
	v_mfma_f32_16x16x32_bf16 v[70:73], v[172:175], v[244:247], v[70:73]
	v_mfma_f32_16x16x32_bf16 v[66:69], v[180:183], v[244:247], v[66:69]
	s_barrier
; #define PG8_STAGE(bufoff, gbase, voff) do { _Pragma("unroll") for (int _i = 0; _i < 2; ++_i) \
;         __builtin_amdgcn_global_load_lds((const unsigned*)((const char*)(gbase) + (voff)[_i]), (PG8_LAS unsigned*)(lds + (bufoff) + ldsw + _i * 8192), 16, 0, 0); } while (0)
; #define PG8_LDA(dst, b, h) do { _Pragma("unroll") for (int m = 0; m < 4; ++m) _Pragma("unroll") for (int k = 0; k < 2; ++k) dst[m][k] = *(const PG8_LAS bf16x8*)(lds + PG8_SA(b, h) + aoff + m * 2048 + k * 1024); } while (0)
; #define PG8_MMA(ai, bj, At, Bt) do { __builtin_amdgcn_s_setprio(1); _Pragma("unroll") for (int m = 0; m < 4; ++m) _Pragma("unroll") for (int n = 0; n < 2; ++n) _Pragma("unroll") for (int k = 0; k < 2; ++k) \
;         acc[ai][bj][m][n] = __builtin_amdgcn_mfma_f32_16x16x32_bf16(Bt[n][k], At[m][k], acc[ai][bj][m][n], 0, 0, 0); __builtin_amdgcn_s_setprio(0); } while (0)
; #define PG8_WAIT_V(n) asm volatile("s_waitcnt vmcnt(" #n ")" ::: "memory")
; #define PG8_WAIT_L(n) asm volatile("s_waitcnt lgkmcnt(" #n ")" ::: "memory")
; #define PG8_BAR __builtin_amdgcn_s_barrier()
; #define PG8_SCHED __builtin_amdgcn_sched_barrier(0)
; template <class Epi, class Sched, bool ALIGN_EPI = false, bool SP2 = false>
; __device__ __forceinline__ void gemm_phase(PG8_LAS unsigned char* lds, const Gemm g, const Sched& S, const Epi& E) {
;     ...
;             PG8_LDA(At, 1, 1); PG8_STAGE(PG8_SB(1, 0), b3, voffB); PG8_STAGE(PG8_SB(1, 1), b3 + hstepB, voffB); PG8_STAGE(PG8_SA(1, 0), a3, voffA);
;             PG8_WAIT_V(8); PG8_WAIT_L(0); PG8_BAR; PG8_MMA(1, 0, At, B0); PG8_MMA(1, 1, At, B1); PG8_BAR; PG8_SCHED;
	s_add_i32 s9, s9, s42
	v_lshl_add_u64 v[184:185], v[184:185], 0, s[60:61]
	s_mov_b32 m0, s9
	ds_read_b128 v[194:197], v151 offset:49152
	ds_read_b128 v[206:209], v151 offset:50176
	ds_read_b128 v[210:213], v151 offset:51200
	ds_read_b128 v[214:217], v151 offset:52224
	ds_read_b128 v[218:221], v151 offset:53248
	ds_read_b128 v[236:239], v151 offset:54272
	ds_read_b128 v[240:243], v151 offset:55296
	ds_read_b128 v[244:247], v151 offset:56320
	global_load_lds_dwordx4 v[184:185], off
	s_add_i32 m0, s9, 0x2000
	s_add_u32 s10, s84, 0x20080
	v_lshl_add_u64 v[184:185], v[198:199], 0, s[60:61]
	s_addc_u32 s11, s85, 0
	s_add_i32 s9, s12, s42
	global_load_lds_dwordx4 v[184:185], off
	s_mov_b32 m0, s9
	v_lshl_add_u64 v[184:185], s[10:11], 0, v[130:131]
	global_load_lds_dwordx4 v[184:185], off
	s_add_i32 m0, s9, 0x2000
	v_lshl_add_u64 v[184:185], s[10:11], 0, v[134:135]
	global_load_lds_dwordx4 v[184:185], off
	s_mov_b32 m0, s82
	v_lshl_add_u64 v[184:185], v[222:223], 0, s[60:61]
	global_load_lds_dwordx4 v[184:185], off
	s_mov_b32 m0, s86
	v_lshl_add_u64 v[184:185], v[234:235], 0, s[60:61]
	global_load_lds_dwordx4 v[184:185], off
	s_waitcnt vmcnt(8)
	s_waitcnt lgkmcnt(0)
	s_barrier
	v_mfma_f32_16x16x32_bf16 v[62:65], v[152:155], v[194:197], v[62:65]
	v_mfma_f32_16x16x32_bf16 v[58:61], v[160:163], v[194:197], v[58:61]
	v_mfma_f32_16x16x32_bf16 v[54:57], v[152:155], v[210:213], v[54:57]
	v_mfma_f32_16x16x32_bf16 v[50:53], v[160:163], v[210:213], v[50:53]
	v_mfma_f32_16x16x32_bf16 v[46:49], v[152:155], v[218:221], v[46:49]
	v_mfma_f32_16x16x32_bf16 v[42:45], v[160:163], v[218:221], v[42:45]
	v_mfma_f32_16x16x32_bf16 v[38:41], v[152:155], v[240:243], v[38:41]
	v_mfma_f32_16x16x32_bf16 v[34:37], v[160:163], v[240:243], v[34:37]
	v_mfma_f32_16x16x32_bf16 v[62:65], v[156:159], v[206:209], v[62:65]
	v_mfma_f32_16x16x32_bf16 v[58:61], v[164:167], v[206:209], v[58:61]
	v_mfma_f32_16x16x32_bf16 v[54:57], v[156:159], v[214:217], v[54:57]
	v_mfma_f32_16x16x32_bf16 v[50:53], v[164:167], v[214:217], v[50:53]
	v_mfma_f32_16x16x32_bf16 v[46:49], v[156:159], v[236:239], v[46:49]
	v_mfma_f32_16x16x32_bf16 v[42:45], v[164:167], v[236:239], v[42:45]
	v_mfma_f32_16x16x32_bf16 v[38:41], v[156:159], v[244:247], v[38:41]
	v_mfma_f32_16x16x32_bf16 v[34:37], v[164:167], v[244:247], v[34:37]
	v_mfma_f32_16x16x32_bf16 v[30:33], v[168:171], v[194:197], v[30:33]
	v_mfma_f32_16x16x32_bf16 v[26:29], v[176:179], v[194:197], v[26:29]
	v_mfma_f32_16x16x32_bf16 v[22:25], v[168:171], v[210:213], v[22:25]
	v_mfma_f32_16x16x32_bf16 v[18:21], v[176:179], v[210:213], v[18:21]
	v_mfma_f32_16x16x32_bf16 v[14:17], v[168:171], v[218:221], v[14:17]
	v_mfma_f32_16x16x32_bf16 v[10:13], v[176:179], v[218:221], v[10:13]
	v_mfma_f32_16x16x32_bf16 v[6:9], v[168:171], v[240:243], v[6:9]
	v_mfma_f32_16x16x32_bf16 v[2:5], v[176:179], v[240:243], v[2:5]
	v_mfma_f32_16x16x32_bf16 v[30:33], v[172:175], v[206:209], v[30:33]
	v_mfma_f32_16x16x32_bf16 v[26:29], v[180:183], v[206:209], v[26:29]
	v_mfma_f32_16x16x32_bf16 v[22:25], v[172:175], v[214:217], v[22:25]
	v_mfma_f32_16x16x32_bf16 v[18:21], v[180:183], v[214:217], v[18:21]
	v_mfma_f32_16x16x32_bf16 v[14:17], v[172:175], v[236:239], v[14:17]
	v_mfma_f32_16x16x32_bf16 v[10:13], v[180:183], v[236:239], v[10:13]
	v_mfma_f32_16x16x32_bf16 v[6:9], v[172:175], v[244:247], v[6:9]
	v_mfma_f32_16x16x32_bf16 v[2:5], v[180:183], v[244:247], v[2:5]
	s_barrier
	s_add_i32 s8, s8, 2
	s_add_u32 s80, s80, 0x100
	s_addc_u32 s81, s81, 0
	s_cmp_gt_u32 s8, 29
	s_cbranch_scc0 .LBB0_1233
	s_and_b64 vcc, exec, s[62:63]
	s_cbranch_vccz .LBB0_1236
	s_barrier
